# MLP1 GEMM epilogues: the 8 row sum-of-squares loads requested together instead of one dependent load at a time
# speedup vs baseline: 1.0419x; 1.0165x over previous
.LBB0_130:
	s_add_u32 s8, s60, 0xfffc0080
	s_addc_u32 s9, s61, -1
	s_add_i32 s16, 0, 0x10000
	v_add_u32_e32 v150, s16, v168
	ds_read_b128 v[128:131], v150
	ds_read_b128 v[132:135], v150 offset:1024
	ds_read_b128 v[146:149], v150 offset:2048
	ds_read_b128 v[150:153], v150 offset:3072
	s_cmp_eq_u32 s15, 12
	s_cselect_b32 s9, s5, s9
	s_cselect_b32 s8, s10, s8
	s_cselect_b32 s63, s1, s14
	s_cselect_b32 s62, s12, s13
	v_lshl_add_u64 v[164:165], s[60:61], 0, v[142:143]
	s_add_i32 m0, s38, 0xc000
	ds_read_b128 v[154:157], v170
	ds_read_b128 v[172:175], v170 offset:1024
	ds_read_b128 v[176:179], v170 offset:2048
	ds_read_b128 v[180:183], v170 offset:3072
	ds_read_b128 v[184:187], v170 offset:4096
	ds_read_b128 v[188:191], v170 offset:5120
	ds_read_b128 v[192:195], v170 offset:6144
	ds_read_b128 v[196:199], v170 offset:7168
	global_load_lds_dwordx4 v[164:165], off
	v_lshl_add_u64 v[164:165], s[60:61], 0, v[144:145]
	s_add_i32 m0, s38, 0xe000
	s_nop 0
	global_load_lds_dwordx4 v[164:165], off
	s_waitcnt lgkmcnt(8)
	s_barrier
	s_waitcnt lgkmcnt(0)
	s_setprio 1
	s_waitcnt lgkmcnt(0)
	v_mfma_f32_16x16x32_bf16 v[124:127], v[128:131], v[154:157], v[124:127]
	v_mfma_f32_16x16x32_bf16 v[120:123], v[146:149], v[154:157], v[120:123]
	v_mfma_f32_16x16x32_bf16 v[116:119], v[128:131], v[176:179], v[116:119]
	v_mfma_f32_16x16x32_bf16 v[112:115], v[146:149], v[176:179], v[112:115]
	v_mfma_f32_16x16x32_bf16 v[108:111], v[128:131], v[184:187], v[108:111]
	v_mfma_f32_16x16x32_bf16 v[104:107], v[146:149], v[184:187], v[104:107]
	v_mfma_f32_16x16x32_bf16 v[100:103], v[128:131], v[192:195], v[100:103]
	v_mfma_f32_16x16x32_bf16 v[96:99], v[146:149], v[192:195], v[96:99]
	v_mfma_f32_16x16x32_bf16 v[124:127], v[132:135], v[172:175], v[124:127]
	v_mfma_f32_16x16x32_bf16 v[120:123], v[150:153], v[172:175], v[120:123]
	v_mfma_f32_16x16x32_bf16 v[116:119], v[132:135], v[180:183], v[116:119]
	v_mfma_f32_16x16x32_bf16 v[112:115], v[150:153], v[180:183], v[112:115]
	v_mfma_f32_16x16x32_bf16 v[108:111], v[132:135], v[188:191], v[108:111]
	v_mfma_f32_16x16x32_bf16 v[104:107], v[150:153], v[188:191], v[104:107]
	v_mfma_f32_16x16x32_bf16 v[100:103], v[132:135], v[196:199], v[100:103]
	v_mfma_f32_16x16x32_bf16 v[96:99], v[150:153], v[196:199], v[96:99]
	s_setprio 0
	s_barrier
	s_add_i32 s18, 0, 0x14000
	s_add_i32 s16, s16, s37
	v_add_u32_e32 v158, s18, v168
	v_lshl_add_u64 v[164:165], s[62:63], 0, v[160:161]
	s_mov_b32 m0, s16
	ds_read_b128 v[200:203], v158
	ds_read_b128 v[204:207], v158 offset:1024
	ds_read_b128 v[208:211], v158 offset:2048
	ds_read_b128 v[212:215], v158 offset:3072
	global_load_lds_dwordx4 v[164:165], off
	v_lshl_add_u64 v[166:167], s[62:63], 0, v[136:137]
	s_add_i32 m0, s16, 0x2000
	s_nop 0
	global_load_lds_dwordx4 v[166:167], off
	s_barrier
	s_waitcnt lgkmcnt(0)
	s_setprio 1
	s_waitcnt lgkmcnt(0)
	v_mfma_f32_16x16x32_bf16 v[68:71], v[200:203], v[154:157], v[68:71]
	v_mfma_f32_16x16x32_bf16 v[64:67], v[208:211], v[154:157], v[64:67]
	v_mfma_f32_16x16x32_bf16 v[52:55], v[200:203], v[176:179], v[52:55]
	v_mfma_f32_16x16x32_bf16 v[48:51], v[208:211], v[176:179], v[48:51]
	v_mfma_f32_16x16x32_bf16 v[44:47], v[200:203], v[184:187], v[44:47]
	v_mfma_f32_16x16x32_bf16 v[40:43], v[208:211], v[184:187], v[40:43]
	v_mfma_f32_16x16x32_bf16 v[36:39], v[200:203], v[192:195], v[36:39]
	v_mfma_f32_16x16x32_bf16 v[32:35], v[208:211], v[192:195], v[32:35]
	v_mfma_f32_16x16x32_bf16 v[68:71], v[204:207], v[172:175], v[68:71]
	v_mfma_f32_16x16x32_bf16 v[64:67], v[212:215], v[172:175], v[64:67]
	v_mfma_f32_16x16x32_bf16 v[52:55], v[204:207], v[180:183], v[52:55]
	v_mfma_f32_16x16x32_bf16 v[48:51], v[212:215], v[180:183], v[48:51]
	v_mfma_f32_16x16x32_bf16 v[44:47], v[204:207], v[188:191], v[44:47]
	v_mfma_f32_16x16x32_bf16 v[40:43], v[212:215], v[188:191], v[40:43]
	v_mfma_f32_16x16x32_bf16 v[36:39], v[204:207], v[196:199], v[36:39]
	v_mfma_f32_16x16x32_bf16 v[32:35], v[212:215], v[196:199], v[32:35]
	s_setprio 0
	s_mov_b32 m0, s38
	v_lshl_add_u64 v[216:217], s[8:9], 0, v[140:141]
	s_barrier
	ds_read_b128 v[154:157], v170 offset:16384
	ds_read_b128 v[172:175], v170 offset:17408
	ds_read_b128 v[176:179], v170 offset:18432
	ds_read_b128 v[180:183], v170 offset:19456
	ds_read_b128 v[184:187], v170 offset:20480
	ds_read_b128 v[188:191], v170 offset:21504
	ds_read_b128 v[192:195], v170 offset:22528
	ds_read_b128 v[196:199], v170 offset:23552
	global_load_lds_dwordx4 v[216:217], off
	v_lshl_add_u64 v[218:219], s[8:9], 0, v[138:139]
	s_mov_b32 m0, s39
	s_nop 0
	global_load_lds_dwordx4 v[218:219], off
	s_barrier
	s_waitcnt lgkmcnt(0)
	s_setprio 1
	s_waitcnt lgkmcnt(0)
	v_mfma_f32_16x16x32_bf16 v[92:95], v[128:131], v[154:157], v[92:95]
	v_mfma_f32_16x16x32_bf16 v[88:91], v[146:149], v[154:157], v[88:91]
	v_mfma_f32_16x16x32_bf16 v[84:87], v[128:131], v[176:179], v[84:87]
	v_mfma_f32_16x16x32_bf16 v[80:83], v[146:149], v[176:179], v[80:83]
	v_mfma_f32_16x16x32_bf16 v[76:79], v[128:131], v[184:187], v[76:79]
	v_mfma_f32_16x16x32_bf16 v[72:75], v[146:149], v[184:187], v[72:75]
	v_mfma_f32_16x16x32_bf16 v[60:63], v[128:131], v[192:195], v[60:63]
	v_mfma_f32_16x16x32_bf16 v[56:59], v[146:149], v[192:195], v[56:59]
	v_mfma_f32_16x16x32_bf16 v[92:95], v[132:135], v[172:175], v[92:95]
	v_mfma_f32_16x16x32_bf16 v[88:91], v[150:153], v[172:175], v[88:91]
	v_mfma_f32_16x16x32_bf16 v[84:87], v[132:135], v[180:183], v[84:87]
	v_mfma_f32_16x16x32_bf16 v[80:83], v[150:153], v[180:183], v[80:83]
	v_mfma_f32_16x16x32_bf16 v[76:79], v[132:135], v[188:191], v[76:79]
	v_mfma_f32_16x16x32_bf16 v[72:75], v[150:153], v[188:191], v[72:75]
	v_mfma_f32_16x16x32_bf16 v[60:63], v[132:135], v[196:199], v[60:63]
	v_mfma_f32_16x16x32_bf16 v[56:59], v[150:153], v[196:199], v[56:59]
	s_setprio 0
	s_barrier
	s_add_u32 s16, s62, 0x40000
	s_addc_u32 s17, s63, 0
	s_add_i32 s18, s18, s37
	v_lshl_add_u64 v[128:129], s[16:17], 0, v[160:161]
	s_mov_b32 m0, s18
	s_nop 0
	global_load_lds_dwordx4 v[128:129], off
	v_lshl_add_u64 v[128:129], s[16:17], 0, v[136:137]
	s_add_i32 m0, s18, 0x2000
	s_nop 0
	global_load_lds_dwordx4 v[128:129], off
	s_waitcnt vmcnt(6)
	s_barrier
	s_setprio 1
	v_mfma_f32_16x16x32_bf16 v[28:31], v[200:203], v[154:157], v[28:31]
	v_mfma_f32_16x16x32_bf16 v[24:27], v[208:211], v[154:157], v[24:27]
	v_mfma_f32_16x16x32_bf16 v[20:23], v[200:203], v[176:179], v[20:23]
	v_mfma_f32_16x16x32_bf16 v[16:19], v[208:211], v[176:179], v[16:19]
	v_mfma_f32_16x16x32_bf16 v[12:15], v[200:203], v[184:187], v[12:15]
	v_mfma_f32_16x16x32_bf16 v[8:11], v[208:211], v[184:187], v[8:11]
	v_mfma_f32_16x16x32_bf16 v[4:7], v[200:203], v[192:195], v[4:7]
	v_mfma_f32_16x16x32_bf16 v[0:3], v[208:211], v[192:195], v[0:3]
	v_mfma_f32_16x16x32_bf16 v[28:31], v[204:207], v[172:175], v[28:31]
	v_mfma_f32_16x16x32_bf16 v[24:27], v[212:215], v[172:175], v[24:27]
	v_mfma_f32_16x16x32_bf16 v[20:23], v[204:207], v[180:183], v[20:23]
	v_mfma_f32_16x16x32_bf16 v[16:19], v[212:215], v[180:183], v[16:19]
	v_mfma_f32_16x16x32_bf16 v[12:15], v[204:207], v[188:191], v[12:15]
	v_mfma_f32_16x16x32_bf16 v[8:11], v[212:215], v[188:191], v[8:11]
	v_mfma_f32_16x16x32_bf16 v[4:7], v[204:207], v[196:199], v[4:7]
	v_mfma_f32_16x16x32_bf16 v[0:3], v[212:215], v[196:199], v[0:3]
	s_setprio 0
	s_add_i32 s16, 0, 0x18000
	v_add_u32_e32 v150, s16, v168
	s_barrier
	ds_read_b128 v[128:131], v150
	ds_read_b128 v[132:135], v150 offset:1024
	ds_read_b128 v[146:149], v150 offset:2048
	ds_read_b128 v[150:153], v150 offset:3072
	s_add_u32 s8, s8, 0x40000
	s_addc_u32 s9, s9, 0
	s_mov_b32 m0, s40
	v_lshl_add_u64 v[200:201], s[8:9], 0, v[140:141]
	ds_read_b128 v[154:157], v170 offset:32768
	ds_read_b128 v[172:175], v170 offset:33792
	ds_read_b128 v[176:179], v170 offset:34816
	ds_read_b128 v[180:183], v170 offset:35840
	ds_read_b128 v[184:187], v170 offset:36864
	ds_read_b128 v[188:191], v170 offset:37888
	ds_read_b128 v[192:195], v170 offset:38912
	ds_read_b128 v[196:199], v170 offset:39936
	global_load_lds_dwordx4 v[200:201], off
	v_lshl_add_u64 v[200:201], s[8:9], 0, v[138:139]
	s_mov_b32 m0, s41
	s_nop 0
	global_load_lds_dwordx4 v[200:201], off
	s_waitcnt lgkmcnt(8)
	s_barrier
	s_waitcnt lgkmcnt(0)
	s_setprio 1
	s_waitcnt lgkmcnt(0)
	v_mfma_f32_16x16x32_bf16 v[124:127], v[128:131], v[154:157], v[124:127]
	v_mfma_f32_16x16x32_bf16 v[120:123], v[146:149], v[154:157], v[120:123]
	v_mfma_f32_16x16x32_bf16 v[116:119], v[128:131], v[176:179], v[116:119]
	v_mfma_f32_16x16x32_bf16 v[112:115], v[146:149], v[176:179], v[112:115]
	v_mfma_f32_16x16x32_bf16 v[108:111], v[128:131], v[184:187], v[108:111]
	v_mfma_f32_16x16x32_bf16 v[104:107], v[146:149], v[184:187], v[104:107]
	v_mfma_f32_16x16x32_bf16 v[100:103], v[128:131], v[192:195], v[100:103]
	v_mfma_f32_16x16x32_bf16 v[96:99], v[146:149], v[192:195], v[96:99]
	v_mfma_f32_16x16x32_bf16 v[124:127], v[132:135], v[172:175], v[124:127]
	v_mfma_f32_16x16x32_bf16 v[120:123], v[150:153], v[172:175], v[120:123]
	v_mfma_f32_16x16x32_bf16 v[116:119], v[132:135], v[180:183], v[116:119]
	v_mfma_f32_16x16x32_bf16 v[112:115], v[150:153], v[180:183], v[112:115]
	v_mfma_f32_16x16x32_bf16 v[108:111], v[132:135], v[188:191], v[108:111]
	v_mfma_f32_16x16x32_bf16 v[104:107], v[150:153], v[188:191], v[104:107]
	v_mfma_f32_16x16x32_bf16 v[100:103], v[132:135], v[196:199], v[100:103]
	v_mfma_f32_16x16x32_bf16 v[96:99], v[150:153], v[196:199], v[96:99]
	s_setprio 0
	s_barrier
	s_add_i32 s17, 0, 0x1c000
	s_add_i32 s8, s16, s37
	v_add_u32_e32 v158, s17, v168
	v_lshl_add_u64 v[164:165], v[164:165], 0, s[74:75]
	s_mov_b32 m0, s8
	ds_read_b128 v[200:203], v158
	ds_read_b128 v[204:207], v158 offset:1024
	ds_read_b128 v[208:211], v158 offset:2048
	ds_read_b128 v[212:215], v158 offset:3072
	global_load_lds_dwordx4 v[164:165], off
	v_lshl_add_u64 v[164:165], v[166:167], 0, s[74:75]
	s_add_i32 m0, s8, 0x2000
	s_nop 0
	global_load_lds_dwordx4 v[164:165], off
	s_barrier
	s_waitcnt lgkmcnt(0)
	s_setprio 1
	s_waitcnt lgkmcnt(0)
	v_mfma_f32_16x16x32_bf16 v[68:71], v[200:203], v[154:157], v[68:71]
	v_mfma_f32_16x16x32_bf16 v[64:67], v[208:211], v[154:157], v[64:67]
	v_mfma_f32_16x16x32_bf16 v[52:55], v[200:203], v[176:179], v[52:55]
	v_mfma_f32_16x16x32_bf16 v[48:51], v[208:211], v[176:179], v[48:51]
	v_mfma_f32_16x16x32_bf16 v[44:47], v[200:203], v[184:187], v[44:47]
	v_mfma_f32_16x16x32_bf16 v[40:43], v[208:211], v[184:187], v[40:43]
	v_mfma_f32_16x16x32_bf16 v[36:39], v[200:203], v[192:195], v[36:39]
	v_mfma_f32_16x16x32_bf16 v[32:35], v[208:211], v[192:195], v[32:35]
	v_mfma_f32_16x16x32_bf16 v[68:71], v[204:207], v[172:175], v[68:71]
	v_mfma_f32_16x16x32_bf16 v[64:67], v[212:215], v[172:175], v[64:67]
	v_mfma_f32_16x16x32_bf16 v[52:55], v[204:207], v[180:183], v[52:55]
	v_mfma_f32_16x16x32_bf16 v[48:51], v[212:215], v[180:183], v[48:51]
	v_mfma_f32_16x16x32_bf16 v[44:47], v[204:207], v[188:191], v[44:47]
	v_mfma_f32_16x16x32_bf16 v[40:43], v[212:215], v[188:191], v[40:43]
	v_mfma_f32_16x16x32_bf16 v[36:39], v[204:207], v[196:199], v[36:39]
	v_mfma_f32_16x16x32_bf16 v[32:35], v[212:215], v[196:199], v[32:35]
	s_setprio 0
	s_mov_b32 m0, s42
	v_lshl_add_u64 v[164:165], v[216:217], 0, s[74:75]
	s_barrier
	ds_read_b128 v[154:157], v170 offset:49152
	ds_read_b128 v[172:175], v170 offset:50176
	ds_read_b128 v[176:179], v170 offset:51200
	ds_read_b128 v[180:183], v170 offset:52224
	ds_read_b128 v[184:187], v170 offset:53248
	ds_read_b128 v[188:191], v170 offset:54272
	ds_read_b128 v[192:195], v170 offset:55296
	ds_read_b128 v[196:199], v170 offset:56320
	global_load_lds_dwordx4 v[164:165], off
	v_lshl_add_u64 v[164:165], v[218:219], 0, s[74:75]
	s_mov_b32 m0, s43
	s_nop 0
	global_load_lds_dwordx4 v[164:165], off
	s_barrier
	s_waitcnt lgkmcnt(0)
	s_setprio 1
	s_waitcnt lgkmcnt(0)
	v_mfma_f32_16x16x32_bf16 v[92:95], v[128:131], v[154:157], v[92:95]
	v_mfma_f32_16x16x32_bf16 v[88:91], v[146:149], v[154:157], v[88:91]
	v_mfma_f32_16x16x32_bf16 v[84:87], v[128:131], v[176:179], v[84:87]
	v_mfma_f32_16x16x32_bf16 v[80:83], v[146:149], v[176:179], v[80:83]
	v_mfma_f32_16x16x32_bf16 v[76:79], v[128:131], v[184:187], v[76:79]
	v_mfma_f32_16x16x32_bf16 v[72:75], v[146:149], v[184:187], v[72:75]
	v_mfma_f32_16x16x32_bf16 v[60:63], v[128:131], v[192:195], v[60:63]
	v_mfma_f32_16x16x32_bf16 v[56:59], v[146:149], v[192:195], v[56:59]
	v_mfma_f32_16x16x32_bf16 v[92:95], v[132:135], v[172:175], v[92:95]
	v_mfma_f32_16x16x32_bf16 v[88:91], v[150:153], v[172:175], v[88:91]
	v_mfma_f32_16x16x32_bf16 v[84:87], v[132:135], v[180:183], v[84:87]
	v_mfma_f32_16x16x32_bf16 v[80:83], v[150:153], v[180:183], v[80:83]
	v_mfma_f32_16x16x32_bf16 v[76:79], v[132:135], v[188:191], v[76:79]
	v_mfma_f32_16x16x32_bf16 v[72:75], v[150:153], v[188:191], v[72:75]
	v_mfma_f32_16x16x32_bf16 v[60:63], v[132:135], v[196:199], v[60:63]
	v_mfma_f32_16x16x32_bf16 v[56:59], v[150:153], v[196:199], v[56:59]
	s_setprio 0
	s_barrier
	s_add_u32 s8, s62, 0x40080
	s_addc_u32 s9, s63, 0
	s_add_i32 s16, s17, s37
	v_lshl_add_u64 v[128:129], s[8:9], 0, v[160:161]
	s_mov_b32 m0, s16
	s_nop 0
	global_load_lds_dwordx4 v[128:129], off
	v_lshl_add_u64 v[128:129], s[8:9], 0, v[136:137]
	s_add_i32 m0, s16, 0x2000
	s_nop 0
	global_load_lds_dwordx4 v[128:129], off
	s_waitcnt vmcnt(6)
	s_barrier
	s_setprio 1
	v_mfma_f32_16x16x32_bf16 v[28:31], v[200:203], v[154:157], v[28:31]
	v_mfma_f32_16x16x32_bf16 v[24:27], v[208:211], v[154:157], v[24:27]
	v_mfma_f32_16x16x32_bf16 v[20:23], v[200:203], v[176:179], v[20:23]
	v_mfma_f32_16x16x32_bf16 v[16:19], v[208:211], v[176:179], v[16:19]
	v_mfma_f32_16x16x32_bf16 v[12:15], v[200:203], v[184:187], v[12:15]
	v_mfma_f32_16x16x32_bf16 v[8:11], v[208:211], v[184:187], v[8:11]
	v_mfma_f32_16x16x32_bf16 v[4:7], v[200:203], v[192:195], v[4:7]
	v_mfma_f32_16x16x32_bf16 v[0:3], v[208:211], v[192:195], v[0:3]
	v_mfma_f32_16x16x32_bf16 v[28:31], v[204:207], v[172:175], v[28:31]
	v_mfma_f32_16x16x32_bf16 v[24:27], v[212:215], v[172:175], v[24:27]
	v_mfma_f32_16x16x32_bf16 v[20:23], v[204:207], v[180:183], v[20:23]
	v_mfma_f32_16x16x32_bf16 v[16:19], v[212:215], v[180:183], v[16:19]
	v_mfma_f32_16x16x32_bf16 v[12:15], v[204:207], v[188:191], v[12:15]
	v_mfma_f32_16x16x32_bf16 v[8:11], v[212:215], v[188:191], v[8:11]
	v_mfma_f32_16x16x32_bf16 v[4:7], v[204:207], v[196:199], v[4:7]
	v_mfma_f32_16x16x32_bf16 v[0:3], v[212:215], v[196:199], v[0:3]
	s_setprio 0
	s_add_i32 s15, s15, 2
	s_add_u32 s60, s60, 0x100
	s_addc_u32 s61, s61, 0
	s_add_u32 s13, s13, 0x100
	s_addc_u32 s14, s14, 0
	s_cmp_gt_u32 s15, 13
	s_barrier
	s_cbranch_scc0 .LBB0_130
	v_lshl_add_u32 v146, s65, 8, v159
	v_readlane_b32 s8, v250, 14
	v_ashrrev_i32_e32 v147, 31, v146
	v_readlane_b32 s9, v250, 15
	v_readlane_b32 s1, v250, 16
	v_lshl_or_b32 v156, s66, 8, v169
	v_lshl_add_u64 v[128:129], v[146:147], 3, s[8:9]
	global_load_dwordx2 v[130:131], v[128:129], off
	global_load_dwordx2 v[218:219], v[128:129], off offset:128
	global_load_dwordx2 v[220:221], v[128:129], off offset:256
	global_load_dwordx2 v[222:223], v[128:129], off offset:384
	global_load_dwordx2 v[224:225], v[128:129], off offset:1024
	global_load_dwordx2 v[226:227], v[128:129], off offset:1152
	global_load_dwordx2 v[228:229], v[128:129], off offset:1280
	global_load_dwordx2 v[230:231], v[128:129], off offset:1408
	s_ashr_i32 s8, s65, 5
	s_ashr_i32 s9, s8, 31
	s_lshl_b64 s[8:9], s[8:9], 14
	s_add_u32 s8, s1, s8
	v_readlane_b32 s1, v250, 17
	v_ashrrev_i32_e32 v157, 31, v156
	s_addc_u32 s9, s1, s9
	v_lshl_add_u64 v[164:165], v[156:157], 2, s[8:9]
	v_readlane_b32 s8, v253, 29
	v_readlane_b32 s9, v253, 30
	s_mov_b32 s1, 0x100000
	s_mov_b32 s66, s0
	s_mov_b32 s65, s4
	s_mov_b64 s[20:21], s[6:7]
	v_readlane_b32 s62, v255, 4
	v_readlane_b32 s63, v255, 5
	s_waitcnt vmcnt(0)
	v_ffbh_u32_e32 v132, v131
	v_min_u32_e32 v132, 32, v132
	v_lshlrev_b64 v[130:131], v132, v[130:131]
	v_min_u32_e32 v130, 1, v130
	v_or_b32_e32 v130, v131, v130
	v_cvt_f32_u32_e32 v130, v130
	v_sub_u32_e32 v131, 32, v132
	v_ldexp_f32 v130, v130, v131
	v_mul_f32_e32 v130, 0x37800000, v130
	v_fmamk_f32 v158, v130, 0x3a800000, v240
	v_mov_b32_e32 v130, v218
	v_mov_b32_e32 v131, v219
	v_cmp_gt_f32_e32 vcc, s53, v158
	v_mul_f32_e32 v162, 0x4b800000, v158
	v_ffbh_u32_e32 v132, v131
	v_min_u32_e32 v132, 32, v132
	v_lshlrev_b64 v[130:131], v132, v[130:131]
	v_min_u32_e32 v130, 1, v130
	v_or_b32_e32 v130, v131, v130
	v_cvt_f32_u32_e32 v130, v130
	v_sub_u32_e32 v131, 32, v132
	v_cndmask_b32_e32 v158, v158, v162, vcc
	v_rsq_f32_e32 v158, v158
	v_ldexp_f32 v130, v130, v131
	v_mul_f32_e32 v130, 0x37800000, v130
	v_fmamk_f32 v171, v130, 0x3a800000, v240
	v_mov_b32_e32 v130, v220
	v_mov_b32_e32 v131, v221
	v_mul_f32_e32 v162, 0x45800000, v158
	v_cndmask_b32_e32 v184, v158, v162, vcc
	v_cmp_gt_f32_e32 vcc, s53, v171
	v_mul_f32_e32 v158, 0x4b800000, v171
	v_ffbh_u32_e32 v132, v131
	v_min_u32_e32 v132, 32, v132
	v_lshlrev_b64 v[130:131], v132, v[130:131]
	v_min_u32_e32 v130, 1, v130
	v_or_b32_e32 v130, v131, v130
	v_cvt_f32_u32_e32 v130, v130
	v_sub_u32_e32 v131, 32, v132
	v_cndmask_b32_e32 v158, v171, v158, vcc
	v_rsq_f32_e32 v158, v158
	v_ldexp_f32 v130, v130, v131
	v_mul_f32_e32 v130, 0x37800000, v130
	v_fmamk_f32 v172, v130, 0x3a800000, v240
	v_mov_b32_e32 v130, v222
	v_mov_b32_e32 v131, v223
	v_mul_f32_e32 v162, 0x45800000, v158
	v_cndmask_b32_e32 v182, v158, v162, vcc
	v_cmp_gt_f32_e32 vcc, s53, v172
	v_mul_f32_e32 v158, 0x4b800000, v172
	v_ffbh_u32_e32 v132, v131
	v_min_u32_e32 v132, 32, v132
	v_lshlrev_b64 v[130:131], v132, v[130:131]
	v_min_u32_e32 v130, 1, v130
	v_or_b32_e32 v130, v131, v130
	v_cvt_f32_u32_e32 v130, v130
	v_sub_u32_e32 v131, 32, v132
	v_cndmask_b32_e32 v158, v172, v158, vcc
	v_rsq_f32_e32 v158, v158
	v_ldexp_f32 v130, v130, v131
	v_mul_f32_e32 v130, 0x37800000, v130
	v_fmamk_f32 v173, v130, 0x3a800000, v240
	v_mov_b32_e32 v130, v224
	v_mov_b32_e32 v131, v225
	v_mul_f32_e32 v162, 0x45800000, v158
	v_cndmask_b32_e32 v180, v158, v162, vcc
	v_cmp_gt_f32_e32 vcc, s53, v173
	v_mul_f32_e32 v158, 0x4b800000, v173
	v_ffbh_u32_e32 v132, v131
	v_min_u32_e32 v132, 32, v132
	v_lshlrev_b64 v[130:131], v132, v[130:131]
	v_min_u32_e32 v130, 1, v130
	v_or_b32_e32 v130, v131, v130
	v_cvt_f32_u32_e32 v130, v130
	v_sub_u32_e32 v131, 32, v132
	v_cndmask_b32_e32 v158, v173, v158, vcc
	v_rsq_f32_e32 v158, v158
	v_ldexp_f32 v130, v130, v131
	v_mul_f32_e32 v130, 0x37800000, v130
	v_fmamk_f32 v174, v130, 0x3a800000, v240
	v_mov_b32_e32 v130, v226
	v_mov_b32_e32 v131, v227
	v_mul_f32_e32 v162, 0x45800000, v158
	v_cndmask_b32_e32 v178, v158, v162, vcc
	v_cmp_gt_f32_e32 vcc, s53, v174
	v_mul_f32_e32 v158, 0x4b800000, v174
	v_ffbh_u32_e32 v132, v131
	v_min_u32_e32 v132, 32, v132
	v_lshlrev_b64 v[130:131], v132, v[130:131]
	v_min_u32_e32 v130, 1, v130
	v_or_b32_e32 v130, v131, v130
	v_cvt_f32_u32_e32 v130, v130
	v_sub_u32_e32 v131, 32, v132
	v_cndmask_b32_e32 v158, v174, v158, vcc
	v_rsq_f32_e32 v158, v158
	v_ldexp_f32 v130, v130, v131
	v_mul_f32_e32 v130, 0x37800000, v130
	v_fmamk_f32 v175, v130, 0x3a800000, v240
	v_mov_b32_e32 v130, v228
	v_mov_b32_e32 v131, v229
	v_mul_f32_e32 v162, 0x45800000, v158
	v_mov_b32_e32 v128, v230
	v_mov_b32_e32 v129, v231
	v_cndmask_b32_e32 v176, v158, v162, vcc
	v_cmp_gt_f32_e32 vcc, s53, v175
	v_mul_f32_e32 v158, 0x4b800000, v175
	v_ffbh_u32_e32 v132, v131
	v_min_u32_e32 v132, 32, v132
	v_lshlrev_b64 v[130:131], v132, v[130:131]
	v_min_u32_e32 v130, 1, v130
	v_or_b32_e32 v130, v131, v130
	v_cvt_f32_u32_e32 v130, v130
	v_sub_u32_e32 v131, 32, v132
	v_cndmask_b32_e32 v158, v175, v158, vcc
	v_rsq_f32_e32 v158, v158
	v_ldexp_f32 v130, v130, v131
	v_mul_f32_e32 v130, 0x37800000, v130
	v_fmamk_f32 v177, v130, 0x3a800000, v240
	v_ffbh_u32_e32 v130, v129
	v_min_u32_e32 v130, 32, v130
	v_lshlrev_b64 v[128:129], v130, v[128:129]
	v_min_u32_e32 v128, 1, v128
	v_or_b32_e32 v128, v129, v128
	v_cvt_f32_u32_e32 v128, v128
	v_sub_u32_e32 v129, 32, v130
	v_mul_f32_e32 v162, 0x45800000, v158
	v_cndmask_b32_e32 v174, v158, v162, vcc
	v_ldexp_f32 v128, v128, v129
	v_mul_f32_e32 v128, 0x37800000, v128
	v_fmamk_f32 v179, v128, 0x3a800000, v240
	global_load_dwordx4 v[128:131], v[164:165], off offset:16
	global_load_dwordx4 v[132:135], v[164:165], off
	v_cmp_gt_f32_e32 vcc, s53, v177
	v_mul_f32_e32 v158, 0x4b800000, v177
	s_waitcnt vmcnt(0)
	v_pk_add_f32 v[148:149], v[130:131], 0 op_sel_hi:[1,0]
	v_pk_add_f32 v[152:153], v[134:135], 0 op_sel_hi:[1,0]
	v_pk_add_f32 v[154:155], v[132:133], 0 op_sel_hi:[1,0]
	v_pk_add_f32 v[150:151], v[128:129], 0 op_sel_hi:[1,0]
	global_load_dwordx4 v[128:131], v[164:165], off offset:528
	global_load_dwordx4 v[132:135], v[164:165], off offset:512
	v_cndmask_b32_e32 v158, v177, v158, vcc
	v_rsq_f32_e32 v158, v158
	v_pk_fma_f32 v[122:123], v[122:123], v[184:185], v[148:149] op_sel_hi:[1,0,1]
	v_pk_fma_f32 v[126:127], v[126:127], v[184:185], v[152:153] op_sel_hi:[1,0,1]
	v_pk_fma_f32 v[124:125], v[124:125], v[184:185], v[154:155] op_sel_hi:[1,0,1]
	v_mul_f32_e32 v162, 0x45800000, v158
	v_cndmask_b32_e32 v172, v158, v162, vcc
	v_cmp_gt_f32_e32 vcc, s53, v179
	v_mul_f32_e32 v158, 0x4b800000, v179
	v_pk_fma_f32 v[120:121], v[120:121], v[184:185], v[150:151] op_sel_hi:[1,0,1]
	v_cndmask_b32_e32 v158, v179, v158, vcc
	v_rsq_f32_e32 v158, v158
	v_max_f32_e32 v122, 0, v122
	v_max_f32_e32 v124, 0, v124
	v_max_f32_e32 v120, 0, v120
	v_mul_f32_e32 v162, 0x45800000, v158
	v_cndmask_b32_e32 v158, v158, v162, vcc
	v_max_f32_e32 v121, 0, v121
	v_mul_f32_e32 v162, v122, v122
	v_max_f32_e32 v122, 0, v127
	v_mul_f32_e32 v124, v124, v124
	v_mul_f32_e32 v120, v120, v120
	v_max_f32_e32 v125, 0, v125
	v_mul_f32_e32 v121, v121, v121
	v_max_f32_e32 v126, 0, v126
	v_mul_f32_e32 v127, v122, v122
	v_max_f32_e32 v122, 0, v123
	v_mul_f32_e32 v125, v125, v125
	v_mul_f32_e32 v126, v126, v126
	v_mul_f32_e32 v164, v122, v122
	v_cvt_pk_bf16_f32 v122, v124, v125
	v_cvt_pk_bf16_f32 v123, v126, v127
	v_cvt_pk_bf16_f32 v124, v120, v121
	v_lshlrev_b64 v[120:121], 13, v[146:147]
	v_lshl_add_u64 v[120:121], s[8:9], 0, v[120:121]
	v_lshlrev_b64 v[126:127], 1, v[156:157]
	v_pk_fma_f32 v[114:115], v[114:115], v[182:183], v[148:149] op_sel_hi:[1,0,1]
	v_lshl_add_u64 v[120:121], v[120:121], 0, v[126:127]
	v_pk_fma_f32 v[118:119], v[118:119], v[182:183], v[152:153] op_sel_hi:[1,0,1]
	v_pk_fma_f32 v[116:117], v[116:117], v[182:183], v[154:155] op_sel_hi:[1,0,1]
	v_pk_fma_f32 v[112:113], v[112:113], v[182:183], v[150:151] op_sel_hi:[1,0,1]
	v_max_f32_e32 v114, 0, v114
	v_cvt_pk_bf16_f32 v125, v162, v164
	global_store_dwordx4 v[120:121], v[122:125], off
	v_max_f32_e32 v116, 0, v116
	v_max_f32_e32 v112, 0, v112
	v_mul_f32_e32 v122, v114, v114
	v_max_f32_e32 v114, 0, v119
	v_mul_f32_e32 v116, v116, v116
	v_mul_f32_e32 v112, v112, v112
	v_max_f32_e32 v117, 0, v117
	v_max_f32_e32 v113, 0, v113
	v_max_f32_e32 v118, 0, v118
	v_mul_f32_e32 v119, v114, v114
	v_max_f32_e32 v114, 0, v115
	v_mul_f32_e32 v117, v117, v117
	v_mul_f32_e32 v113, v113, v113
	v_mul_f32_e32 v118, v118, v118
	v_mul_f32_e32 v123, v114, v114
	v_cvt_pk_bf16_f32 v114, v116, v117
	v_cvt_pk_bf16_f32 v115, v118, v119
	v_cvt_pk_bf16_f32 v116, v112, v113
	v_or_b32_e32 v112, 16, v146
	v_ashrrev_i32_e32 v113, 31, v112
	v_lshlrev_b64 v[112:113], 13, v[112:113]
	v_lshl_add_u64 v[112:113], s[8:9], 0, v[112:113]
	v_pk_fma_f32 v[106:107], v[106:107], v[180:181], v[148:149] op_sel_hi:[1,0,1]
	v_lshl_add_u64 v[112:113], v[112:113], 0, v[126:127]
	v_pk_fma_f32 v[110:111], v[110:111], v[180:181], v[152:153] op_sel_hi:[1,0,1]
	v_pk_fma_f32 v[108:109], v[108:109], v[180:181], v[154:155] op_sel_hi:[1,0,1]
	v_pk_fma_f32 v[104:105], v[104:105], v[180:181], v[150:151] op_sel_hi:[1,0,1]
	v_max_f32_e32 v106, 0, v106
	v_cvt_pk_bf16_f32 v117, v122, v123
	global_store_dwordx4 v[112:113], v[114:117], off
	v_max_f32_e32 v108, 0, v108
	v_max_f32_e32 v104, 0, v104
	v_mul_f32_e32 v114, v106, v106
	v_max_f32_e32 v106, 0, v111
	v_mul_f32_e32 v108, v108, v108
	v_mul_f32_e32 v104, v104, v104
	v_max_f32_e32 v109, 0, v109
	v_max_f32_e32 v105, 0, v105
	v_max_f32_e32 v110, 0, v110
	v_mul_f32_e32 v111, v106, v106
	v_max_f32_e32 v106, 0, v107
	v_mul_f32_e32 v109, v109, v109
	v_mul_f32_e32 v105, v105, v105
	v_mul_f32_e32 v110, v110, v110
	v_mul_f32_e32 v115, v106, v106
	v_cvt_pk_bf16_f32 v106, v108, v109
	v_cvt_pk_bf16_f32 v107, v110, v111
	v_cvt_pk_bf16_f32 v108, v104, v105
	v_or_b32_e32 v104, 32, v146
	v_ashrrev_i32_e32 v105, 31, v104
	v_lshlrev_b64 v[104:105], 13, v[104:105]
	v_lshl_add_u64 v[104:105], s[8:9], 0, v[104:105]
	v_pk_fma_f32 v[98:99], v[98:99], v[178:179], v[148:149] op_sel_hi:[1,0,1]
	v_lshl_add_u64 v[104:105], v[104:105], 0, v[126:127]
	v_pk_fma_f32 v[102:103], v[102:103], v[178:179], v[152:153] op_sel_hi:[1,0,1]
	v_pk_fma_f32 v[100:101], v[100:101], v[178:179], v[154:155] op_sel_hi:[1,0,1]
	v_pk_fma_f32 v[96:97], v[96:97], v[178:179], v[150:151] op_sel_hi:[1,0,1]
	v_max_f32_e32 v98, 0, v98
	v_cvt_pk_bf16_f32 v109, v114, v115
	global_store_dwordx4 v[104:105], v[106:109], off
	v_max_f32_e32 v100, 0, v100
	v_max_f32_e32 v96, 0, v96
	v_mul_f32_e32 v106, v98, v98
	v_max_f32_e32 v98, 0, v103
	v_mul_f32_e32 v100, v100, v100
	v_mul_f32_e32 v96, v96, v96
	v_max_f32_e32 v101, 0, v101
	v_max_f32_e32 v97, 0, v97
	v_max_f32_e32 v102, 0, v102
	v_mul_f32_e32 v103, v98, v98
	v_max_f32_e32 v98, 0, v99
	v_mul_f32_e32 v101, v101, v101
	v_mul_f32_e32 v97, v97, v97
	v_mul_f32_e32 v102, v102, v102
	v_mul_f32_e32 v107, v98, v98
	v_cvt_pk_bf16_f32 v98, v100, v101
	v_cvt_pk_bf16_f32 v99, v102, v103
	v_cvt_pk_bf16_f32 v100, v96, v97
	v_or_b32_e32 v96, 48, v146
	v_ashrrev_i32_e32 v97, 31, v96
	v_lshlrev_b64 v[96:97], 13, v[96:97]
	v_lshl_add_u64 v[96:97], s[8:9], 0, v[96:97]
	v_pk_fma_f32 v[90:91], v[90:91], v[176:177], v[148:149] op_sel_hi:[1,0,1]
	v_lshl_add_u64 v[96:97], v[96:97], 0, v[126:127]
	v_pk_fma_f32 v[94:95], v[94:95], v[176:177], v[152:153] op_sel_hi:[1,0,1]
	v_max_f32_e32 v90, 0, v90
	v_cvt_pk_bf16_f32 v101, v106, v107
	global_store_dwordx4 v[96:97], v[98:101], off
	v_pk_fma_f32 v[92:93], v[92:93], v[176:177], v[154:155] op_sel_hi:[1,0,1]
	v_max_f32_e32 v94, 0, v94
	v_mul_f32_e32 v98, v90, v90
	v_max_f32_e32 v90, 0, v95
	v_max_f32_e32 v92, 0, v92
	v_max_f32_e32 v93, 0, v93
	v_mul_f32_e32 v94, v94, v94
	v_mul_f32_e32 v95, v90, v90
	v_max_f32_e32 v90, 0, v91
	v_pk_fma_f32 v[88:89], v[88:89], v[176:177], v[150:151] op_sel_hi:[1,0,1]
	v_mul_f32_e32 v92, v92, v92
	v_mul_f32_e32 v93, v93, v93
	v_mul_f32_e32 v99, v90, v90
	v_cvt_pk_bf16_f32 v90, v92, v93
	v_cvt_pk_bf16_f32 v91, v94, v95
	v_add_co_u32_e32 v94, vcc, s1, v120
	v_pk_fma_f32 v[82:83], v[82:83], v[174:175], v[148:149] op_sel_hi:[1,0,1]
	v_max_f32_e32 v88, 0, v88
	v_max_f32_e32 v89, 0, v89
	v_addc_co_u32_e32 v95, vcc, 0, v121, vcc
	v_pk_fma_f32 v[86:87], v[86:87], v[174:175], v[152:153] op_sel_hi:[1,0,1]
	v_max_f32_e32 v82, 0, v82
	v_mul_f32_e32 v88, v88, v88
	v_mul_f32_e32 v89, v89, v89
	v_cvt_pk_bf16_f32 v92, v88, v89
	v_cvt_pk_bf16_f32 v93, v98, v99
	global_store_dwordx4 v[94:95], v[90:93], off
	v_pk_fma_f32 v[84:85], v[84:85], v[174:175], v[154:155] op_sel_hi:[1,0,1]
	v_max_f32_e32 v86, 0, v86
	v_mul_f32_e32 v90, v82, v82
	v_max_f32_e32 v82, 0, v87
	v_max_f32_e32 v84, 0, v84
	v_max_f32_e32 v85, 0, v85
	v_mul_f32_e32 v86, v86, v86
	v_mul_f32_e32 v87, v82, v82
	v_max_f32_e32 v82, 0, v83
	s_mov_b32 s1, 0x120000
	v_pk_fma_f32 v[80:81], v[80:81], v[174:175], v[150:151] op_sel_hi:[1,0,1]
	v_mul_f32_e32 v84, v84, v84
	v_mul_f32_e32 v85, v85, v85
	v_mul_f32_e32 v91, v82, v82
	v_cvt_pk_bf16_f32 v82, v84, v85
	v_cvt_pk_bf16_f32 v83, v86, v87
	v_add_co_u32_e32 v86, vcc, s1, v120
	v_pk_fma_f32 v[74:75], v[74:75], v[172:173], v[148:149] op_sel_hi:[1,0,1]
	v_max_f32_e32 v80, 0, v80
	v_max_f32_e32 v81, 0, v81
	v_addc_co_u32_e32 v87, vcc, 0, v121, vcc
	v_pk_fma_f32 v[78:79], v[78:79], v[172:173], v[152:153] op_sel_hi:[1,0,1]
	v_max_f32_e32 v74, 0, v74
	v_mul_f32_e32 v80, v80, v80
	v_mul_f32_e32 v81, v81, v81
	v_cvt_pk_bf16_f32 v84, v80, v81
	v_cvt_pk_bf16_f32 v85, v90, v91
	global_store_dwordx4 v[86:87], v[82:85], off
	v_pk_fma_f32 v[76:77], v[76:77], v[172:173], v[154:155] op_sel_hi:[1,0,1]
	v_max_f32_e32 v78, 0, v78
	v_mul_f32_e32 v82, v74, v74
	v_max_f32_e32 v74, 0, v79
	v_max_f32_e32 v76, 0, v76
	v_max_f32_e32 v77, 0, v77
	v_mul_f32_e32 v78, v78, v78
	v_mul_f32_e32 v79, v74, v74
	v_max_f32_e32 v74, 0, v75
	s_mov_b32 s1, 0x140000
	v_pk_fma_f32 v[72:73], v[72:73], v[172:173], v[150:151] op_sel_hi:[1,0,1]
	v_mul_f32_e32 v76, v76, v76
	v_mul_f32_e32 v77, v77, v77
	v_mul_f32_e32 v83, v74, v74
	v_cvt_pk_bf16_f32 v74, v76, v77
	v_cvt_pk_bf16_f32 v75, v78, v79
	v_add_co_u32_e32 v78, vcc, s1, v120
	v_pk_fma_f32 v[58:59], v[58:59], v[158:159], v[148:149] op_sel_hi:[1,0,1]
	v_max_f32_e32 v72, 0, v72
	v_max_f32_e32 v73, 0, v73
	v_addc_co_u32_e32 v79, vcc, 0, v121, vcc
	v_pk_fma_f32 v[62:63], v[62:63], v[158:159], v[152:153] op_sel_hi:[1,0,1]
	v_max_f32_e32 v58, 0, v58
	v_mul_f32_e32 v72, v72, v72
	v_mul_f32_e32 v73, v73, v73
	v_cvt_pk_bf16_f32 v76, v72, v73
	v_cvt_pk_bf16_f32 v77, v82, v83
	global_store_dwordx4 v[78:79], v[74:77], off
	v_pk_fma_f32 v[60:61], v[60:61], v[158:159], v[154:155] op_sel_hi:[1,0,1]
	v_max_f32_e32 v62, 0, v62
	v_mul_f32_e32 v74, v58, v58
	v_max_f32_e32 v58, 0, v63
	v_max_f32_e32 v60, 0, v60
	v_max_f32_e32 v61, 0, v61
	v_mul_f32_e32 v62, v62, v62
	v_mul_f32_e32 v63, v58, v58
	v_max_f32_e32 v58, 0, v59
	s_mov_b32 s1, 0x160000
	v_pk_fma_f32 v[56:57], v[56:57], v[158:159], v[150:151] op_sel_hi:[1,0,1]
	v_mul_f32_e32 v60, v60, v60
	v_mul_f32_e32 v61, v61, v61
	v_mul_f32_e32 v75, v58, v58
	v_cvt_pk_bf16_f32 v58, v60, v61
	v_cvt_pk_bf16_f32 v59, v62, v63
	v_add_co_u32_e32 v62, vcc, s1, v120
	s_waitcnt vmcnt(7)
	v_pk_add_f32 v[134:135], v[134:135], 0 op_sel_hi:[1,0]
	v_max_f32_e32 v56, 0, v56
	v_max_f32_e32 v57, 0, v57
	v_addc_co_u32_e32 v63, vcc, 0, v121, vcc
	v_pk_add_f32 v[130:131], v[130:131], 0 op_sel_hi:[1,0]
	v_mul_f32_e32 v56, v56, v56
	v_mul_f32_e32 v57, v57, v57
	v_cvt_pk_bf16_f32 v60, v56, v57
	v_cvt_pk_bf16_f32 v61, v74, v75
	global_store_dwordx4 v[62:63], v[58:61], off
	v_pk_fma_f32 v[62:63], v[66:67], v[184:185], v[130:131] op_sel_hi:[1,0,1]
	v_pk_add_f32 v[132:133], v[132:133], 0 op_sel_hi:[1,0]
	v_pk_fma_f32 v[58:59], v[70:71], v[184:185], v[134:135] op_sel_hi:[1,0,1]
	v_pk_add_f32 v[128:129], v[128:129], 0 op_sel_hi:[1,0]
	v_max_f32_e32 v58, 0, v58
	v_mul_f32_e32 v66, v58, v58
	v_max_f32_e32 v58, 0, v62
	v_pk_fma_f32 v[60:61], v[68:69], v[184:185], v[132:133] op_sel_hi:[1,0,1]
	v_mul_f32_e32 v62, v58, v58
	v_max_f32_e32 v58, 0, v59
	v_pk_fma_f32 v[64:65], v[64:65], v[184:185], v[128:129] op_sel_hi:[1,0,1]
	v_max_f32_e32 v60, 0, v60
	v_max_f32_e32 v61, 0, v61
	v_mul_f32_e32 v59, v58, v58
	v_max_f32_e32 v58, 0, v63
	v_pk_fma_f32 v[48:49], v[48:49], v[182:183], v[128:129] op_sel_hi:[1,0,1]
	v_mul_f32_e32 v60, v60, v60
	v_max_f32_e32 v64, 0, v64
	v_mul_f32_e32 v61, v61, v61
	v_max_f32_e32 v65, 0, v65
	v_mul_f32_e32 v63, v58, v58
	v_cvt_pk_bf16_f32 v58, v60, v61
	v_pk_fma_f32 v[52:53], v[52:53], v[182:183], v[132:133] op_sel_hi:[1,0,1]
	v_pk_fma_f32 v[50:51], v[50:51], v[182:183], v[130:131] op_sel_hi:[1,0,1]
	v_max_f32_e32 v48, 0, v48
	v_mul_f32_e32 v64, v64, v64
	v_mul_f32_e32 v65, v65, v65
	v_cvt_pk_bf16_f32 v59, v66, v59
	v_cvt_pk_bf16_f32 v60, v64, v65
	v_cvt_pk_bf16_f32 v61, v62, v63
	global_store_dwordx4 v[120:121], v[58:61], off offset:256
	v_pk_fma_f32 v[54:55], v[54:55], v[182:183], v[134:135] op_sel_hi:[1,0,1]
	v_max_f32_e32 v49, 0, v49
	v_mul_f32_e32 v58, v48, v48
	v_max_f32_e32 v48, 0, v53
	v_max_f32_e32 v50, 0, v50
	v_max_f32_e32 v52, 0, v52
	v_mul_f32_e32 v48, v48, v48
	v_mul_f32_e32 v53, v49, v49
	v_max_f32_e32 v49, 0, v54
	v_mul_f32_e32 v54, v50, v50
	v_max_f32_e32 v50, 0, v55
	v_max_f32_e32 v51, 0, v51
	v_pk_fma_f32 v[40:41], v[40:41], v[180:181], v[128:129] op_sel_hi:[1,0,1]
	v_mul_f32_e32 v52, v52, v52
	v_mul_f32_e32 v49, v49, v49
	v_mul_f32_e32 v50, v50, v50
	v_mul_f32_e32 v51, v51, v51
	v_cvt_pk_bf16_f32 v48, v52, v48
	v_pk_fma_f32 v[44:45], v[44:45], v[180:181], v[132:133] op_sel_hi:[1,0,1]
	v_pk_fma_f32 v[42:43], v[42:43], v[180:181], v[130:131] op_sel_hi:[1,0,1]
	v_max_f32_e32 v40, 0, v40
	v_cvt_pk_bf16_f32 v49, v49, v50
	v_cvt_pk_bf16_f32 v50, v58, v53
	v_cvt_pk_bf16_f32 v51, v54, v51
	global_store_dwordx4 v[112:113], v[48:51], off offset:256
	v_pk_fma_f32 v[46:47], v[46:47], v[180:181], v[134:135] op_sel_hi:[1,0,1]
	v_max_f32_e32 v41, 0, v41
	v_mul_f32_e32 v48, v40, v40
	v_max_f32_e32 v40, 0, v45
	v_max_f32_e32 v42, 0, v42
	v_max_f32_e32 v44, 0, v44
	v_mul_f32_e32 v40, v40, v40
	v_mul_f32_e32 v45, v41, v41
	v_max_f32_e32 v41, 0, v46
	v_mul_f32_e32 v46, v42, v42
	v_max_f32_e32 v42, 0, v47
	v_max_f32_e32 v43, 0, v43
	v_pk_fma_f32 v[32:33], v[32:33], v[178:179], v[128:129] op_sel_hi:[1,0,1]
	v_mul_f32_e32 v44, v44, v44
	v_mul_f32_e32 v41, v41, v41
	v_mul_f32_e32 v42, v42, v42
	v_mul_f32_e32 v43, v43, v43
	v_cvt_pk_bf16_f32 v40, v44, v40
	v_pk_fma_f32 v[36:37], v[36:37], v[178:179], v[132:133] op_sel_hi:[1,0,1]
	v_pk_fma_f32 v[34:35], v[34:35], v[178:179], v[130:131] op_sel_hi:[1,0,1]
	v_max_f32_e32 v32, 0, v32
	v_cvt_pk_bf16_f32 v41, v41, v42
	v_cvt_pk_bf16_f32 v42, v48, v45
	v_cvt_pk_bf16_f32 v43, v46, v43
	global_store_dwordx4 v[104:105], v[40:43], off offset:256
	v_pk_fma_f32 v[38:39], v[38:39], v[178:179], v[134:135] op_sel_hi:[1,0,1]
	v_max_f32_e32 v33, 0, v33
	v_mul_f32_e32 v40, v32, v32
	v_max_f32_e32 v32, 0, v37
	v_max_f32_e32 v34, 0, v34
	v_max_f32_e32 v36, 0, v36
	v_mul_f32_e32 v32, v32, v32
	v_mul_f32_e32 v37, v33, v33
	v_max_f32_e32 v33, 0, v38
	v_mul_f32_e32 v38, v34, v34
	v_max_f32_e32 v34, 0, v39
	v_max_f32_e32 v35, 0, v35
	v_pk_fma_f32 v[24:25], v[24:25], v[176:177], v[128:129] op_sel_hi:[1,0,1]
	v_mul_f32_e32 v36, v36, v36
	v_mul_f32_e32 v33, v33, v33
	v_mul_f32_e32 v34, v34, v34
	v_mul_f32_e32 v35, v35, v35
	v_cvt_pk_bf16_f32 v32, v36, v32
	v_pk_fma_f32 v[28:29], v[28:29], v[176:177], v[132:133] op_sel_hi:[1,0,1]
	v_pk_fma_f32 v[26:27], v[26:27], v[176:177], v[130:131] op_sel_hi:[1,0,1]
	v_max_f32_e32 v24, 0, v24
	v_cvt_pk_bf16_f32 v33, v33, v34
	v_cvt_pk_bf16_f32 v34, v40, v37
	v_cvt_pk_bf16_f32 v35, v38, v35
	global_store_dwordx4 v[96:97], v[32:35], off offset:256
	v_pk_fma_f32 v[30:31], v[30:31], v[176:177], v[134:135] op_sel_hi:[1,0,1]
	v_max_f32_e32 v25, 0, v25
	v_mul_f32_e32 v32, v24, v24
	v_max_f32_e32 v24, 0, v29
	v_max_f32_e32 v26, 0, v26
	s_mov_b64 s[8:9], 0x100000
	v_max_f32_e32 v28, 0, v28
	v_mul_f32_e32 v24, v24, v24
	v_mul_f32_e32 v29, v25, v25
	v_max_f32_e32 v25, 0, v30
	v_mul_f32_e32 v30, v26, v26
	v_max_f32_e32 v26, 0, v31
	v_max_f32_e32 v27, 0, v27
	v_pk_fma_f32 v[16:17], v[16:17], v[174:175], v[128:129] op_sel_hi:[1,0,1]
	v_lshl_add_u64 v[88:89], v[120:121], 0, s[8:9]
	v_mul_f32_e32 v28, v28, v28
	v_mul_f32_e32 v25, v25, v25
	v_mul_f32_e32 v26, v26, v26
	v_mul_f32_e32 v27, v27, v27
	v_cvt_pk_bf16_f32 v24, v28, v24
	v_pk_fma_f32 v[20:21], v[20:21], v[174:175], v[132:133] op_sel_hi:[1,0,1]
	v_pk_fma_f32 v[18:19], v[18:19], v[174:175], v[130:131] op_sel_hi:[1,0,1]
	v_max_f32_e32 v16, 0, v16
	v_cvt_pk_bf16_f32 v25, v25, v26
	v_cvt_pk_bf16_f32 v26, v32, v29
	v_cvt_pk_bf16_f32 v27, v30, v27
	global_store_dwordx4 v[88:89], v[24:27], off offset:256
	v_pk_fma_f32 v[22:23], v[22:23], v[174:175], v[134:135] op_sel_hi:[1,0,1]
	v_max_f32_e32 v17, 0, v17
	v_mul_f32_e32 v24, v16, v16
	v_max_f32_e32 v16, 0, v21
	v_max_f32_e32 v18, 0, v18
	s_mov_b64 s[8:9], 0x120000
	v_max_f32_e32 v20, 0, v20
	v_mul_f32_e32 v16, v16, v16
	v_mul_f32_e32 v21, v17, v17
	v_max_f32_e32 v17, 0, v22
	v_mul_f32_e32 v22, v18, v18
	v_max_f32_e32 v18, 0, v23
	v_max_f32_e32 v19, 0, v19
	v_pk_fma_f32 v[8:9], v[8:9], v[172:173], v[128:129] op_sel_hi:[1,0,1]
	v_lshl_add_u64 v[80:81], v[120:121], 0, s[8:9]
	v_mul_f32_e32 v20, v20, v20
	v_mul_f32_e32 v17, v17, v17
	v_mul_f32_e32 v18, v18, v18
	v_mul_f32_e32 v19, v19, v19
	v_cvt_pk_bf16_f32 v16, v20, v16
	v_pk_fma_f32 v[12:13], v[12:13], v[172:173], v[132:133] op_sel_hi:[1,0,1]
	v_pk_fma_f32 v[10:11], v[10:11], v[172:173], v[130:131] op_sel_hi:[1,0,1]
	v_max_f32_e32 v8, 0, v8
	v_cvt_pk_bf16_f32 v17, v17, v18
	v_cvt_pk_bf16_f32 v18, v24, v21
	v_cvt_pk_bf16_f32 v19, v22, v19
	global_store_dwordx4 v[80:81], v[16:19], off offset:256
	v_pk_fma_f32 v[14:15], v[14:15], v[172:173], v[134:135] op_sel_hi:[1,0,1]
	v_max_f32_e32 v9, 0, v9
	v_mul_f32_e32 v16, v8, v8
	v_max_f32_e32 v8, 0, v13
	v_max_f32_e32 v10, 0, v10
	s_mov_b64 s[8:9], 0x140000
	v_max_f32_e32 v12, 0, v12
	v_mul_f32_e32 v8, v8, v8
	v_mul_f32_e32 v13, v9, v9
	v_max_f32_e32 v9, 0, v14
	v_mul_f32_e32 v14, v10, v10
	v_max_f32_e32 v10, 0, v15
	v_max_f32_e32 v11, 0, v11
	v_pk_fma_f32 v[2:3], v[2:3], v[158:159], v[130:131] op_sel_hi:[1,0,1]
	v_pk_fma_f32 v[0:1], v[0:1], v[158:159], v[128:129] op_sel_hi:[1,0,1]
	v_lshl_add_u64 v[72:73], v[120:121], 0, s[8:9]
	v_mul_f32_e32 v12, v12, v12
	v_mul_f32_e32 v9, v9, v9
	v_mul_f32_e32 v10, v10, v10
	v_mul_f32_e32 v11, v11, v11
	v_cvt_pk_bf16_f32 v8, v12, v8
	v_pk_fma_f32 v[6:7], v[6:7], v[158:159], v[134:135] op_sel_hi:[1,0,1]
	v_pk_fma_f32 v[4:5], v[4:5], v[158:159], v[132:133] op_sel_hi:[1,0,1]
	v_max_f32_e32 v0, 0, v0
	v_max_f32_e32 v1, 0, v1
	v_max_f32_e32 v2, 0, v2
	s_mov_b64 s[8:9], 0x160000
	v_cvt_pk_bf16_f32 v9, v9, v10
	v_cvt_pk_bf16_f32 v10, v16, v13
	v_cvt_pk_bf16_f32 v11, v14, v11
	global_store_dwordx4 v[72:73], v[8:11], off offset:256
	v_max_f32_e32 v3, 0, v3
	v_lshl_add_u64 v[56:57], v[120:121], 0, s[8:9]
	v_mul_f32_e32 v8, v0, v0
	v_max_f32_e32 v0, 0, v5
	v_mul_f32_e32 v5, v1, v1
	v_max_f32_e32 v1, 0, v6
	v_mul_f32_e32 v6, v2, v2
	v_max_f32_e32 v2, 0, v7
	v_max_f32_e32 v4, 0, v4
	v_mul_f32_e32 v0, v0, v0
	v_mul_f32_e32 v1, v1, v1
	v_mul_f32_e32 v2, v2, v2
	v_mul_f32_e32 v3, v3, v3
	s_and_b64 vcc, exec, s[2:3]
	s_mov_b64 s[8:9], s[58:59]
	v_mul_f32_e32 v4, v4, v4
	v_cvt_pk_bf16_f32 v0, v4, v0
	v_cvt_pk_bf16_f32 v1, v1, v2
	v_cvt_pk_bf16_f32 v2, v8, v5
	v_cvt_pk_bf16_f32 v3, v6, v3
	global_store_dwordx4 v[56:57], v[0:3], off offset:256
	s_cbranch_vccz .LBB0_123
	s_waitcnt vmcnt(0)
	s_mov_b32 s90, s62
	s_cmpk_gt_u32 s36, 0xff
	s_cbranch_scc1 .LBB0_134
	s_barrier

.LBB0_350:
	s_add_u32 s8, s60, 0xfffc0080
	s_addc_u32 s9, s61, -1
	s_add_i32 s16, 0, 0x10000
	v_add_u32_e32 v150, s16, v168
	ds_read_b128 v[128:131], v150
	ds_read_b128 v[132:135], v150 offset:1024
	ds_read_b128 v[146:149], v150 offset:2048
	ds_read_b128 v[150:153], v150 offset:3072
	s_cmp_eq_u32 s15, 12
	s_cselect_b32 s9, s5, s9
	s_cselect_b32 s8, s10, s8
	s_cselect_b32 s63, s1, s14
	s_cselect_b32 s62, s12, s13
	v_lshl_add_u64 v[200:201], s[60:61], 0, v[142:143]
	s_add_i32 m0, s38, 0xc000
	ds_read_b128 v[154:157], v170
	ds_read_b128 v[172:175], v170 offset:1024
	ds_read_b128 v[176:179], v170 offset:2048
	ds_read_b128 v[180:183], v170 offset:3072
	ds_read_b128 v[184:187], v170 offset:4096
	ds_read_b128 v[188:191], v170 offset:5120
	ds_read_b128 v[192:195], v170 offset:6144
	ds_read_b128 v[196:199], v170 offset:7168
	global_load_lds_dwordx4 v[200:201], off
	v_lshl_add_u64 v[200:201], s[60:61], 0, v[144:145]
	s_add_i32 m0, s38, 0xe000
	s_nop 0
	global_load_lds_dwordx4 v[200:201], off
	s_waitcnt lgkmcnt(8)
	s_barrier
	s_waitcnt lgkmcnt(0)
	s_setprio 1
	s_waitcnt lgkmcnt(0)
	v_mfma_f32_16x16x32_bf16 v[124:127], v[128:131], v[154:157], v[124:127]
	v_mfma_f32_16x16x32_bf16 v[120:123], v[146:149], v[154:157], v[120:123]
	v_mfma_f32_16x16x32_bf16 v[116:119], v[128:131], v[176:179], v[116:119]
	v_mfma_f32_16x16x32_bf16 v[112:115], v[146:149], v[176:179], v[112:115]
	v_mfma_f32_16x16x32_bf16 v[108:111], v[128:131], v[184:187], v[108:111]
	v_mfma_f32_16x16x32_bf16 v[104:107], v[146:149], v[184:187], v[104:107]
	v_mfma_f32_16x16x32_bf16 v[100:103], v[128:131], v[192:195], v[100:103]
	v_mfma_f32_16x16x32_bf16 v[96:99], v[146:149], v[192:195], v[96:99]
	v_mfma_f32_16x16x32_bf16 v[124:127], v[132:135], v[172:175], v[124:127]
	v_mfma_f32_16x16x32_bf16 v[120:123], v[150:153], v[172:175], v[120:123]
	v_mfma_f32_16x16x32_bf16 v[116:119], v[132:135], v[180:183], v[116:119]
	v_mfma_f32_16x16x32_bf16 v[112:115], v[150:153], v[180:183], v[112:115]
	v_mfma_f32_16x16x32_bf16 v[108:111], v[132:135], v[188:191], v[108:111]
	v_mfma_f32_16x16x32_bf16 v[104:107], v[150:153], v[188:191], v[104:107]
	v_mfma_f32_16x16x32_bf16 v[100:103], v[132:135], v[196:199], v[100:103]
	v_mfma_f32_16x16x32_bf16 v[96:99], v[150:153], v[196:199], v[96:99]
	s_setprio 0
	s_barrier
	s_add_i32 s18, 0, 0x14000
	s_add_i32 s16, s16, s37
	v_add_u32_e32 v158, s18, v168
	v_lshl_add_u64 v[216:217], s[62:63], 0, v[160:161]
	s_mov_b32 m0, s16
	ds_read_b128 v[200:203], v158
	ds_read_b128 v[204:207], v158 offset:1024
	ds_read_b128 v[208:211], v158 offset:2048
	ds_read_b128 v[212:215], v158 offset:3072
	global_load_lds_dwordx4 v[216:217], off
	v_lshl_add_u64 v[218:219], s[62:63], 0, v[136:137]
	s_add_i32 m0, s16, 0x2000
	s_nop 0
	global_load_lds_dwordx4 v[218:219], off
	s_barrier
	s_waitcnt lgkmcnt(0)
	s_setprio 1
	s_waitcnt lgkmcnt(0)
	v_mfma_f32_16x16x32_bf16 v[68:71], v[200:203], v[154:157], v[68:71]
	v_mfma_f32_16x16x32_bf16 v[64:67], v[208:211], v[154:157], v[64:67]
	v_mfma_f32_16x16x32_bf16 v[52:55], v[200:203], v[176:179], v[52:55]
	v_mfma_f32_16x16x32_bf16 v[48:51], v[208:211], v[176:179], v[48:51]
	v_mfma_f32_16x16x32_bf16 v[44:47], v[200:203], v[184:187], v[44:47]
	v_mfma_f32_16x16x32_bf16 v[40:43], v[208:211], v[184:187], v[40:43]
	v_mfma_f32_16x16x32_bf16 v[36:39], v[200:203], v[192:195], v[36:39]
	v_mfma_f32_16x16x32_bf16 v[32:35], v[208:211], v[192:195], v[32:35]
	v_mfma_f32_16x16x32_bf16 v[68:71], v[204:207], v[172:175], v[68:71]
	v_mfma_f32_16x16x32_bf16 v[64:67], v[212:215], v[172:175], v[64:67]
	v_mfma_f32_16x16x32_bf16 v[52:55], v[204:207], v[180:183], v[52:55]
	v_mfma_f32_16x16x32_bf16 v[48:51], v[212:215], v[180:183], v[48:51]
	v_mfma_f32_16x16x32_bf16 v[44:47], v[204:207], v[188:191], v[44:47]
	v_mfma_f32_16x16x32_bf16 v[40:43], v[212:215], v[188:191], v[40:43]
	v_mfma_f32_16x16x32_bf16 v[36:39], v[204:207], v[196:199], v[36:39]
	v_mfma_f32_16x16x32_bf16 v[32:35], v[212:215], v[196:199], v[32:35]
	s_setprio 0
	s_mov_b32 m0, s38
	v_lshl_add_u64 v[220:221], s[8:9], 0, v[140:141]
	s_barrier
	ds_read_b128 v[154:157], v170 offset:16384
	ds_read_b128 v[172:175], v170 offset:17408
	ds_read_b128 v[176:179], v170 offset:18432
	ds_read_b128 v[180:183], v170 offset:19456
	ds_read_b128 v[184:187], v170 offset:20480
	ds_read_b128 v[188:191], v170 offset:21504
	ds_read_b128 v[192:195], v170 offset:22528
	ds_read_b128 v[196:199], v170 offset:23552
	global_load_lds_dwordx4 v[220:221], off
	v_lshl_add_u64 v[222:223], s[8:9], 0, v[138:139]
	s_mov_b32 m0, s39
	s_nop 0
	global_load_lds_dwordx4 v[222:223], off
	s_barrier
	s_waitcnt lgkmcnt(0)
	s_setprio 1
	s_waitcnt lgkmcnt(0)
	v_mfma_f32_16x16x32_bf16 v[92:95], v[128:131], v[154:157], v[92:95]
	v_mfma_f32_16x16x32_bf16 v[88:91], v[146:149], v[154:157], v[88:91]
	v_mfma_f32_16x16x32_bf16 v[84:87], v[128:131], v[176:179], v[84:87]
	v_mfma_f32_16x16x32_bf16 v[80:83], v[146:149], v[176:179], v[80:83]
	v_mfma_f32_16x16x32_bf16 v[76:79], v[128:131], v[184:187], v[76:79]
	v_mfma_f32_16x16x32_bf16 v[72:75], v[146:149], v[184:187], v[72:75]
	v_mfma_f32_16x16x32_bf16 v[60:63], v[128:131], v[192:195], v[60:63]
	v_mfma_f32_16x16x32_bf16 v[56:59], v[146:149], v[192:195], v[56:59]
	v_mfma_f32_16x16x32_bf16 v[92:95], v[132:135], v[172:175], v[92:95]
	v_mfma_f32_16x16x32_bf16 v[88:91], v[150:153], v[172:175], v[88:91]
	v_mfma_f32_16x16x32_bf16 v[84:87], v[132:135], v[180:183], v[84:87]
	v_mfma_f32_16x16x32_bf16 v[80:83], v[150:153], v[180:183], v[80:83]
	v_mfma_f32_16x16x32_bf16 v[76:79], v[132:135], v[188:191], v[76:79]
	v_mfma_f32_16x16x32_bf16 v[72:75], v[150:153], v[188:191], v[72:75]
	v_mfma_f32_16x16x32_bf16 v[60:63], v[132:135], v[196:199], v[60:63]
	v_mfma_f32_16x16x32_bf16 v[56:59], v[150:153], v[196:199], v[56:59]
	s_setprio 0
	s_barrier
	s_add_u32 s16, s62, 0x40000
	s_addc_u32 s17, s63, 0
	s_add_i32 s18, s18, s37
	v_lshl_add_u64 v[128:129], s[16:17], 0, v[160:161]
	s_mov_b32 m0, s18
	s_nop 0
	global_load_lds_dwordx4 v[128:129], off
	v_lshl_add_u64 v[128:129], s[16:17], 0, v[136:137]
	s_add_i32 m0, s18, 0x2000
	s_nop 0
	global_load_lds_dwordx4 v[128:129], off
	s_waitcnt vmcnt(6)
	s_barrier
	s_setprio 1
	v_mfma_f32_16x16x32_bf16 v[28:31], v[200:203], v[154:157], v[28:31]
	v_mfma_f32_16x16x32_bf16 v[24:27], v[208:211], v[154:157], v[24:27]
	v_mfma_f32_16x16x32_bf16 v[20:23], v[200:203], v[176:179], v[20:23]
	v_mfma_f32_16x16x32_bf16 v[16:19], v[208:211], v[176:179], v[16:19]
	v_mfma_f32_16x16x32_bf16 v[12:15], v[200:203], v[184:187], v[12:15]
	v_mfma_f32_16x16x32_bf16 v[8:11], v[208:211], v[184:187], v[8:11]
	v_mfma_f32_16x16x32_bf16 v[4:7], v[200:203], v[192:195], v[4:7]
	v_mfma_f32_16x16x32_bf16 v[0:3], v[208:211], v[192:195], v[0:3]
	v_mfma_f32_16x16x32_bf16 v[28:31], v[204:207], v[172:175], v[28:31]
	v_mfma_f32_16x16x32_bf16 v[24:27], v[212:215], v[172:175], v[24:27]
	v_mfma_f32_16x16x32_bf16 v[20:23], v[204:207], v[180:183], v[20:23]
	v_mfma_f32_16x16x32_bf16 v[16:19], v[212:215], v[180:183], v[16:19]
	v_mfma_f32_16x16x32_bf16 v[12:15], v[204:207], v[188:191], v[12:15]
	v_mfma_f32_16x16x32_bf16 v[8:11], v[212:215], v[188:191], v[8:11]
	v_mfma_f32_16x16x32_bf16 v[4:7], v[204:207], v[196:199], v[4:7]
	v_mfma_f32_16x16x32_bf16 v[0:3], v[212:215], v[196:199], v[0:3]
	s_setprio 0
	s_add_i32 s16, 0, 0x18000
	v_add_u32_e32 v150, s16, v168
	s_barrier
	ds_read_b128 v[128:131], v150
	ds_read_b128 v[132:135], v150 offset:1024
	ds_read_b128 v[146:149], v150 offset:2048
	ds_read_b128 v[150:153], v150 offset:3072
	s_add_u32 s8, s8, 0x40000
	s_addc_u32 s9, s9, 0
	s_mov_b32 m0, s40
	v_lshl_add_u64 v[200:201], s[8:9], 0, v[140:141]
	ds_read_b128 v[154:157], v170 offset:32768
	ds_read_b128 v[172:175], v170 offset:33792
	ds_read_b128 v[176:179], v170 offset:34816
	ds_read_b128 v[180:183], v170 offset:35840
	ds_read_b128 v[184:187], v170 offset:36864
	ds_read_b128 v[188:191], v170 offset:37888
	ds_read_b128 v[192:195], v170 offset:38912
	ds_read_b128 v[196:199], v170 offset:39936
	global_load_lds_dwordx4 v[200:201], off
	v_lshl_add_u64 v[200:201], s[8:9], 0, v[138:139]
	s_mov_b32 m0, s41
	s_nop 0
	global_load_lds_dwordx4 v[200:201], off
	s_waitcnt lgkmcnt(8)
	s_barrier
	s_waitcnt lgkmcnt(0)
	s_setprio 1
	s_waitcnt lgkmcnt(0)
	v_mfma_f32_16x16x32_bf16 v[124:127], v[128:131], v[154:157], v[124:127]
	v_mfma_f32_16x16x32_bf16 v[120:123], v[146:149], v[154:157], v[120:123]
	v_mfma_f32_16x16x32_bf16 v[116:119], v[128:131], v[176:179], v[116:119]
	v_mfma_f32_16x16x32_bf16 v[112:115], v[146:149], v[176:179], v[112:115]
	v_mfma_f32_16x16x32_bf16 v[108:111], v[128:131], v[184:187], v[108:111]
	v_mfma_f32_16x16x32_bf16 v[104:107], v[146:149], v[184:187], v[104:107]
	v_mfma_f32_16x16x32_bf16 v[100:103], v[128:131], v[192:195], v[100:103]
	v_mfma_f32_16x16x32_bf16 v[96:99], v[146:149], v[192:195], v[96:99]
	v_mfma_f32_16x16x32_bf16 v[124:127], v[132:135], v[172:175], v[124:127]
	v_mfma_f32_16x16x32_bf16 v[120:123], v[150:153], v[172:175], v[120:123]
	v_mfma_f32_16x16x32_bf16 v[116:119], v[132:135], v[180:183], v[116:119]
	v_mfma_f32_16x16x32_bf16 v[112:115], v[150:153], v[180:183], v[112:115]
	v_mfma_f32_16x16x32_bf16 v[108:111], v[132:135], v[188:191], v[108:111]
	v_mfma_f32_16x16x32_bf16 v[104:107], v[150:153], v[188:191], v[104:107]
	v_mfma_f32_16x16x32_bf16 v[100:103], v[132:135], v[196:199], v[100:103]
	v_mfma_f32_16x16x32_bf16 v[96:99], v[150:153], v[196:199], v[96:99]
	s_setprio 0
	s_barrier
	s_add_i32 s17, 0, 0x1c000
	s_add_i32 s8, s16, s37
	v_add_u32_e32 v158, s17, v168
	v_lshl_add_u64 v[216:217], v[216:217], 0, s[74:75]
	s_mov_b32 m0, s8
	ds_read_b128 v[200:203], v158
	ds_read_b128 v[204:207], v158 offset:1024
	ds_read_b128 v[208:211], v158 offset:2048
	ds_read_b128 v[212:215], v158 offset:3072
	global_load_lds_dwordx4 v[216:217], off
	v_lshl_add_u64 v[216:217], v[218:219], 0, s[74:75]
	s_add_i32 m0, s8, 0x2000
	s_nop 0
	global_load_lds_dwordx4 v[216:217], off
	s_barrier
	s_waitcnt lgkmcnt(0)
	s_setprio 1
	s_waitcnt lgkmcnt(0)
	v_mfma_f32_16x16x32_bf16 v[68:71], v[200:203], v[154:157], v[68:71]
	v_mfma_f32_16x16x32_bf16 v[64:67], v[208:211], v[154:157], v[64:67]
	v_mfma_f32_16x16x32_bf16 v[52:55], v[200:203], v[176:179], v[52:55]
	v_mfma_f32_16x16x32_bf16 v[48:51], v[208:211], v[176:179], v[48:51]
	v_mfma_f32_16x16x32_bf16 v[44:47], v[200:203], v[184:187], v[44:47]
	v_mfma_f32_16x16x32_bf16 v[40:43], v[208:211], v[184:187], v[40:43]
	v_mfma_f32_16x16x32_bf16 v[36:39], v[200:203], v[192:195], v[36:39]
	v_mfma_f32_16x16x32_bf16 v[32:35], v[208:211], v[192:195], v[32:35]
	v_mfma_f32_16x16x32_bf16 v[68:71], v[204:207], v[172:175], v[68:71]
	v_mfma_f32_16x16x32_bf16 v[64:67], v[212:215], v[172:175], v[64:67]
	v_mfma_f32_16x16x32_bf16 v[52:55], v[204:207], v[180:183], v[52:55]
	v_mfma_f32_16x16x32_bf16 v[48:51], v[212:215], v[180:183], v[48:51]
	v_mfma_f32_16x16x32_bf16 v[44:47], v[204:207], v[188:191], v[44:47]
	v_mfma_f32_16x16x32_bf16 v[40:43], v[212:215], v[188:191], v[40:43]
	v_mfma_f32_16x16x32_bf16 v[36:39], v[204:207], v[196:199], v[36:39]
	v_mfma_f32_16x16x32_bf16 v[32:35], v[212:215], v[196:199], v[32:35]
	s_setprio 0
	s_mov_b32 m0, s42
	v_lshl_add_u64 v[216:217], v[220:221], 0, s[74:75]
	s_barrier
	ds_read_b128 v[154:157], v170 offset:49152
	ds_read_b128 v[172:175], v170 offset:50176
	ds_read_b128 v[176:179], v170 offset:51200
	ds_read_b128 v[180:183], v170 offset:52224
	ds_read_b128 v[184:187], v170 offset:53248
	ds_read_b128 v[188:191], v170 offset:54272
	ds_read_b128 v[192:195], v170 offset:55296
	ds_read_b128 v[196:199], v170 offset:56320
	global_load_lds_dwordx4 v[216:217], off
	v_lshl_add_u64 v[216:217], v[222:223], 0, s[74:75]
	s_mov_b32 m0, s43
	s_nop 0
	global_load_lds_dwordx4 v[216:217], off
	s_barrier
	s_waitcnt lgkmcnt(0)
	s_setprio 1
	s_waitcnt lgkmcnt(0)
	v_mfma_f32_16x16x32_bf16 v[92:95], v[128:131], v[154:157], v[92:95]
	v_mfma_f32_16x16x32_bf16 v[88:91], v[146:149], v[154:157], v[88:91]
	v_mfma_f32_16x16x32_bf16 v[84:87], v[128:131], v[176:179], v[84:87]
	v_mfma_f32_16x16x32_bf16 v[80:83], v[146:149], v[176:179], v[80:83]
	v_mfma_f32_16x16x32_bf16 v[76:79], v[128:131], v[184:187], v[76:79]
	v_mfma_f32_16x16x32_bf16 v[72:75], v[146:149], v[184:187], v[72:75]
	v_mfma_f32_16x16x32_bf16 v[60:63], v[128:131], v[192:195], v[60:63]
	v_mfma_f32_16x16x32_bf16 v[56:59], v[146:149], v[192:195], v[56:59]
	v_mfma_f32_16x16x32_bf16 v[92:95], v[132:135], v[172:175], v[92:95]
	v_mfma_f32_16x16x32_bf16 v[88:91], v[150:153], v[172:175], v[88:91]
	v_mfma_f32_16x16x32_bf16 v[84:87], v[132:135], v[180:183], v[84:87]
	v_mfma_f32_16x16x32_bf16 v[80:83], v[150:153], v[180:183], v[80:83]
	v_mfma_f32_16x16x32_bf16 v[76:79], v[132:135], v[188:191], v[76:79]
	v_mfma_f32_16x16x32_bf16 v[72:75], v[150:153], v[188:191], v[72:75]
	v_mfma_f32_16x16x32_bf16 v[60:63], v[132:135], v[196:199], v[60:63]
	v_mfma_f32_16x16x32_bf16 v[56:59], v[150:153], v[196:199], v[56:59]
	s_setprio 0
	s_barrier
	s_add_u32 s8, s62, 0x40080
	s_addc_u32 s9, s63, 0
	s_add_i32 s16, s17, s37
	v_lshl_add_u64 v[128:129], s[8:9], 0, v[160:161]
	s_mov_b32 m0, s16
	s_nop 0
	global_load_lds_dwordx4 v[128:129], off
	v_lshl_add_u64 v[128:129], s[8:9], 0, v[136:137]
	s_add_i32 m0, s16, 0x2000
	s_nop 0
	global_load_lds_dwordx4 v[128:129], off
	s_waitcnt vmcnt(6)
	s_barrier
	s_setprio 1
	v_mfma_f32_16x16x32_bf16 v[28:31], v[200:203], v[154:157], v[28:31]
	v_mfma_f32_16x16x32_bf16 v[24:27], v[208:211], v[154:157], v[24:27]
	v_mfma_f32_16x16x32_bf16 v[20:23], v[200:203], v[176:179], v[20:23]
	v_mfma_f32_16x16x32_bf16 v[16:19], v[208:211], v[176:179], v[16:19]
	v_mfma_f32_16x16x32_bf16 v[12:15], v[200:203], v[184:187], v[12:15]
	v_mfma_f32_16x16x32_bf16 v[8:11], v[208:211], v[184:187], v[8:11]
	v_mfma_f32_16x16x32_bf16 v[4:7], v[200:203], v[192:195], v[4:7]
	v_mfma_f32_16x16x32_bf16 v[0:3], v[208:211], v[192:195], v[0:3]
	v_mfma_f32_16x16x32_bf16 v[28:31], v[204:207], v[172:175], v[28:31]
	v_mfma_f32_16x16x32_bf16 v[24:27], v[212:215], v[172:175], v[24:27]
	v_mfma_f32_16x16x32_bf16 v[20:23], v[204:207], v[180:183], v[20:23]
	v_mfma_f32_16x16x32_bf16 v[16:19], v[212:215], v[180:183], v[16:19]
	v_mfma_f32_16x16x32_bf16 v[12:15], v[204:207], v[188:191], v[12:15]
	v_mfma_f32_16x16x32_bf16 v[8:11], v[212:215], v[188:191], v[8:11]
	v_mfma_f32_16x16x32_bf16 v[4:7], v[204:207], v[196:199], v[4:7]
	v_mfma_f32_16x16x32_bf16 v[0:3], v[212:215], v[196:199], v[0:3]
	s_setprio 0
	s_add_i32 s15, s15, 2
	s_add_u32 s60, s60, 0x100
	s_addc_u32 s61, s61, 0
	s_add_u32 s13, s13, 0x100
	s_addc_u32 s14, s14, 0
	s_cmp_gt_u32 s15, 13
	s_barrier
	s_cbranch_scc0 .LBB0_350
	v_lshl_add_u32 v146, s65, 8, v159
	v_readlane_b32 s8, v249, 24
	v_ashrrev_i32_e32 v147, 31, v146
	v_readlane_b32 s9, v249, 25
	v_readlane_b32 s12, v249, 26
	v_lshl_or_b32 v156, s66, 8, v169
	v_lshl_add_u64 v[128:129], v[146:147], 3, s[8:9]
	global_load_dwordx2 v[130:131], v[128:129], off
	global_load_dwordx2 v[218:219], v[128:129], off offset:128
	global_load_dwordx2 v[220:221], v[128:129], off offset:256
	global_load_dwordx2 v[222:223], v[128:129], off offset:384
	global_load_dwordx2 v[224:225], v[128:129], off offset:1024
	global_load_dwordx2 v[226:227], v[128:129], off offset:1152
	global_load_dwordx2 v[228:229], v[128:129], off offset:1280
	global_load_dwordx2 v[230:231], v[128:129], off offset:1408
	s_ashr_i32 s8, s65, 5
	s_ashr_i32 s9, s8, 31
	s_lshl_b64 s[8:9], s[8:9], 14
	v_readlane_b32 s13, v249, 27
	s_add_u32 s8, s12, s8
	v_ashrrev_i32_e32 v157, 31, v156
	s_addc_u32 s9, s13, s9
	v_lshl_add_u64 v[180:181], v[156:157], 2, s[8:9]
	v_readlane_b32 s8, v253, 29
	v_readlane_b32 s9, v253, 30
	s_mov_b32 s1, 0x100000
	s_mov_b32 s66, s0
	s_mov_b32 s65, s4
	s_mov_b64 s[20:21], s[6:7]
	v_readlane_b32 s62, v255, 4
	v_readlane_b32 s63, v255, 5
	s_waitcnt vmcnt(0)
	v_ffbh_u32_e32 v132, v131
	v_min_u32_e32 v132, 32, v132
	v_lshlrev_b64 v[130:131], v132, v[130:131]
	v_min_u32_e32 v130, 1, v130
	v_or_b32_e32 v130, v131, v130
	v_cvt_f32_u32_e32 v130, v130
	v_sub_u32_e32 v131, 32, v132
	v_ldexp_f32 v130, v130, v131
	v_mul_f32_e32 v130, 0x37800000, v130
	v_fmamk_f32 v158, v130, 0x3a800000, v240
	v_mov_b32_e32 v130, v218
	v_mov_b32_e32 v131, v219
	v_cmp_gt_f32_e32 vcc, s53, v158
	v_mul_f32_e32 v164, 0x4b800000, v158
	v_ffbh_u32_e32 v132, v131
	v_min_u32_e32 v132, 32, v132
	v_lshlrev_b64 v[130:131], v132, v[130:131]
	v_min_u32_e32 v130, 1, v130
	v_or_b32_e32 v130, v131, v130
	v_cvt_f32_u32_e32 v130, v130
	v_sub_u32_e32 v131, 32, v132
	v_cndmask_b32_e32 v158, v158, v164, vcc
	v_rsq_f32_e32 v158, v158
	v_ldexp_f32 v130, v130, v131
	v_mul_f32_e32 v130, 0x37800000, v130
	v_fmamk_f32 v171, v130, 0x3a800000, v240
	v_mov_b32_e32 v130, v220
	v_mov_b32_e32 v131, v221
	v_mul_f32_e32 v164, 0x45800000, v158
	v_cndmask_b32_e32 v184, v158, v164, vcc
	v_cmp_gt_f32_e32 vcc, s53, v171
	v_mul_f32_e32 v158, 0x4b800000, v171
	v_ffbh_u32_e32 v132, v131
	v_min_u32_e32 v132, 32, v132
	v_lshlrev_b64 v[130:131], v132, v[130:131]
	v_min_u32_e32 v130, 1, v130
	v_or_b32_e32 v130, v131, v130
	v_cvt_f32_u32_e32 v130, v130
	v_sub_u32_e32 v131, 32, v132
	v_cndmask_b32_e32 v158, v171, v158, vcc
	v_rsq_f32_e32 v158, v158
	v_ldexp_f32 v130, v130, v131
	v_mul_f32_e32 v130, 0x37800000, v130
	v_fmamk_f32 v172, v130, 0x3a800000, v240
	v_mov_b32_e32 v130, v222
	v_mov_b32_e32 v131, v223
	v_mul_f32_e32 v164, 0x45800000, v158
	v_cndmask_b32_e32 v182, v158, v164, vcc
	v_cmp_gt_f32_e32 vcc, s53, v172
	v_mul_f32_e32 v158, 0x4b800000, v172
	v_ffbh_u32_e32 v132, v131
	v_min_u32_e32 v132, 32, v132
	v_lshlrev_b64 v[130:131], v132, v[130:131]
	v_min_u32_e32 v130, 1, v130
	v_or_b32_e32 v130, v131, v130
	v_cvt_f32_u32_e32 v130, v130
	v_sub_u32_e32 v131, 32, v132
	v_cndmask_b32_e32 v158, v172, v158, vcc
	v_rsq_f32_e32 v158, v158
	v_ldexp_f32 v130, v130, v131
	v_mul_f32_e32 v130, 0x37800000, v130
	v_fmamk_f32 v173, v130, 0x3a800000, v240
	v_mov_b32_e32 v130, v224
	v_mov_b32_e32 v131, v225
	v_mul_f32_e32 v164, 0x45800000, v158
	v_ffbh_u32_e32 v132, v131
	v_min_u32_e32 v132, 32, v132
	v_lshlrev_b64 v[130:131], v132, v[130:131]
	v_min_u32_e32 v130, 1, v130
	v_or_b32_e32 v130, v131, v130
	v_cvt_f32_u32_e32 v130, v130
	v_sub_u32_e32 v131, 32, v132
	v_ldexp_f32 v130, v130, v131
	v_mul_f32_e32 v130, 0x37800000, v130
	v_fmamk_f32 v174, v130, 0x3a800000, v240
	v_mov_b32_e32 v130, v226
	v_mov_b32_e32 v131, v227
	v_ffbh_u32_e32 v132, v131
	v_min_u32_e32 v132, 32, v132
	v_lshlrev_b64 v[130:131], v132, v[130:131]
	v_min_u32_e32 v130, 1, v130
	v_or_b32_e32 v130, v131, v130
	v_cvt_f32_u32_e32 v130, v130
	v_sub_u32_e32 v131, 32, v132
	v_ldexp_f32 v130, v130, v131
	v_mul_f32_e32 v130, 0x37800000, v130
	v_fmamk_f32 v175, v130, 0x3a800000, v240
	v_mov_b32_e32 v130, v228
	v_mov_b32_e32 v131, v229
	v_ffbh_u32_e32 v132, v131
	v_mov_b32_e32 v128, v230
	v_mov_b32_e32 v129, v231
	v_min_u32_e32 v132, 32, v132
	v_lshlrev_b64 v[130:131], v132, v[130:131]
	v_min_u32_e32 v130, 1, v130
	v_or_b32_e32 v130, v131, v130
	v_cvt_f32_u32_e32 v130, v130
	v_sub_u32_e32 v131, 32, v132
	v_ldexp_f32 v130, v130, v131
	v_mul_f32_e32 v130, 0x37800000, v130
	v_fmamk_f32 v177, v130, 0x3a800000, v240
	v_ffbh_u32_e32 v130, v129
	v_min_u32_e32 v130, 32, v130
	v_lshlrev_b64 v[128:129], v130, v[128:129]
	v_min_u32_e32 v128, 1, v128
	v_or_b32_e32 v128, v129, v128
	v_cvt_f32_u32_e32 v128, v128
	v_sub_u32_e32 v129, 32, v130
	v_ldexp_f32 v128, v128, v129
	v_mul_f32_e32 v128, 0x37800000, v128
	v_fmamk_f32 v179, v128, 0x3a800000, v240
	global_load_dwordx4 v[128:131], v[180:181], off offset:16
	global_load_dwordx4 v[132:135], v[180:181], off
	s_waitcnt vmcnt(0)
	v_pk_add_f32 v[148:149], v[130:131], 0 op_sel_hi:[1,0]
	v_pk_add_f32 v[152:153], v[134:135], 0 op_sel_hi:[1,0]
	v_pk_add_f32 v[154:155], v[132:133], 0 op_sel_hi:[1,0]
	v_pk_add_f32 v[150:151], v[128:129], 0 op_sel_hi:[1,0]
	global_load_dwordx4 v[128:131], v[180:181], off offset:528
	global_load_dwordx4 v[132:135], v[180:181], off offset:512
	v_cndmask_b32_e32 v180, v158, v164, vcc
	v_cmp_gt_f32_e32 vcc, s53, v173
	v_mul_f32_e32 v158, 0x4b800000, v173
	v_pk_fma_f32 v[122:123], v[122:123], v[184:185], v[148:149] op_sel_hi:[1,0,1]
	v_cndmask_b32_e32 v158, v173, v158, vcc
	v_rsq_f32_e32 v158, v158
	v_pk_fma_f32 v[126:127], v[126:127], v[184:185], v[152:153] op_sel_hi:[1,0,1]
	v_pk_fma_f32 v[124:125], v[124:125], v[184:185], v[154:155] op_sel_hi:[1,0,1]
	v_pk_fma_f32 v[120:121], v[120:121], v[184:185], v[150:151] op_sel_hi:[1,0,1]
	v_mul_f32_e32 v164, 0x45800000, v158
	v_cndmask_b32_e32 v178, v158, v164, vcc
	v_cmp_gt_f32_e32 vcc, s53, v174
	v_mul_f32_e32 v158, 0x4b800000, v174
	v_max_f32_e32 v122, 0, v122
	v_cndmask_b32_e32 v158, v174, v158, vcc
	v_rsq_f32_e32 v158, v158
	v_max_f32_e32 v124, 0, v124
	v_max_f32_e32 v120, 0, v120
	v_max_f32_e32 v121, 0, v121
	v_mul_f32_e32 v164, 0x45800000, v158
	v_cndmask_b32_e32 v176, v158, v164, vcc
	v_cmp_gt_f32_e32 vcc, s53, v175
	v_mul_f32_e32 v158, 0x4b800000, v175
	v_mul_f32_e32 v124, v124, v124
	v_cndmask_b32_e32 v158, v175, v158, vcc
	v_rsq_f32_e32 v158, v158
	v_mul_f32_e32 v120, v120, v120
	v_max_f32_e32 v125, 0, v125
	v_mul_f32_e32 v121, v121, v121
	v_mul_f32_e32 v164, 0x45800000, v158
	v_cndmask_b32_e32 v174, v158, v164, vcc
	v_cmp_gt_f32_e32 vcc, s53, v177
	v_mul_f32_e32 v158, 0x4b800000, v177
	v_max_f32_e32 v126, 0, v126
	v_cndmask_b32_e32 v158, v177, v158, vcc
	v_rsq_f32_e32 v158, v158
	v_mul_f32_e32 v125, v125, v125
	v_mul_f32_e32 v126, v126, v126
	v_pk_fma_f32 v[114:115], v[114:115], v[182:183], v[148:149] op_sel_hi:[1,0,1]
	v_mul_f32_e32 v164, 0x45800000, v158
	v_cndmask_b32_e32 v172, v158, v164, vcc
	v_cmp_gt_f32_e32 vcc, s53, v179
	v_mul_f32_e32 v158, 0x4b800000, v179
	v_pk_fma_f32 v[118:119], v[118:119], v[182:183], v[152:153] op_sel_hi:[1,0,1]
	v_cndmask_b32_e32 v158, v179, v158, vcc
	v_rsq_f32_e32 v158, v158
	v_pk_fma_f32 v[116:117], v[116:117], v[182:183], v[154:155] op_sel_hi:[1,0,1]
	v_pk_fma_f32 v[112:113], v[112:113], v[182:183], v[150:151] op_sel_hi:[1,0,1]
	v_max_f32_e32 v114, 0, v114
	v_mul_f32_e32 v164, 0x45800000, v158
	v_cndmask_b32_e32 v158, v158, v164, vcc
	v_mul_f32_e32 v164, v122, v122
	v_max_f32_e32 v122, 0, v127
	v_mul_f32_e32 v127, v122, v122
	v_max_f32_e32 v122, 0, v123
	v_mul_f32_e32 v165, v122, v122
	v_cvt_pk_bf16_f32 v122, v124, v125
	v_cvt_pk_bf16_f32 v123, v126, v127
	v_cvt_pk_bf16_f32 v124, v120, v121
	v_lshlrev_b64 v[120:121], 13, v[146:147]
	v_lshl_add_u64 v[120:121], s[8:9], 0, v[120:121]
	v_lshlrev_b64 v[126:127], 1, v[156:157]
	v_lshl_add_u64 v[120:121], v[120:121], 0, v[126:127]
	v_cvt_pk_bf16_f32 v125, v164, v165
	global_store_dwordx4 v[120:121], v[122:125], off
	v_max_f32_e32 v116, 0, v116
	v_max_f32_e32 v112, 0, v112
	v_mul_f32_e32 v122, v114, v114
	v_max_f32_e32 v114, 0, v119
	v_mul_f32_e32 v116, v116, v116
	v_mul_f32_e32 v112, v112, v112
	v_max_f32_e32 v117, 0, v117
	v_max_f32_e32 v113, 0, v113
	v_max_f32_e32 v118, 0, v118
	v_mul_f32_e32 v119, v114, v114
	v_max_f32_e32 v114, 0, v115
	v_mul_f32_e32 v117, v117, v117
	v_mul_f32_e32 v113, v113, v113
	v_mul_f32_e32 v118, v118, v118
	v_mul_f32_e32 v123, v114, v114
	v_cvt_pk_bf16_f32 v114, v116, v117
	v_cvt_pk_bf16_f32 v115, v118, v119
	v_cvt_pk_bf16_f32 v116, v112, v113
	v_or_b32_e32 v112, 16, v146
	v_ashrrev_i32_e32 v113, 31, v112
	v_lshlrev_b64 v[112:113], 13, v[112:113]
	v_lshl_add_u64 v[112:113], s[8:9], 0, v[112:113]
	v_pk_fma_f32 v[106:107], v[106:107], v[180:181], v[148:149] op_sel_hi:[1,0,1]
	v_lshl_add_u64 v[112:113], v[112:113], 0, v[126:127]
	v_pk_fma_f32 v[110:111], v[110:111], v[180:181], v[152:153] op_sel_hi:[1,0,1]
	v_pk_fma_f32 v[108:109], v[108:109], v[180:181], v[154:155] op_sel_hi:[1,0,1]
	v_pk_fma_f32 v[104:105], v[104:105], v[180:181], v[150:151] op_sel_hi:[1,0,1]
	v_max_f32_e32 v106, 0, v106
	v_cvt_pk_bf16_f32 v117, v122, v123
	global_store_dwordx4 v[112:113], v[114:117], off
	v_max_f32_e32 v108, 0, v108
	v_max_f32_e32 v104, 0, v104
	v_mul_f32_e32 v114, v106, v106
	v_max_f32_e32 v106, 0, v111
	v_mul_f32_e32 v108, v108, v108
	v_mul_f32_e32 v104, v104, v104
	v_max_f32_e32 v109, 0, v109
	v_max_f32_e32 v105, 0, v105
	v_max_f32_e32 v110, 0, v110
	v_mul_f32_e32 v111, v106, v106
	v_max_f32_e32 v106, 0, v107
	v_mul_f32_e32 v109, v109, v109
	v_mul_f32_e32 v105, v105, v105
	v_mul_f32_e32 v110, v110, v110
	v_mul_f32_e32 v115, v106, v106
	v_cvt_pk_bf16_f32 v106, v108, v109
	v_cvt_pk_bf16_f32 v107, v110, v111
	v_cvt_pk_bf16_f32 v108, v104, v105
	v_or_b32_e32 v104, 32, v146
	v_ashrrev_i32_e32 v105, 31, v104
	v_lshlrev_b64 v[104:105], 13, v[104:105]
	v_lshl_add_u64 v[104:105], s[8:9], 0, v[104:105]
	v_pk_fma_f32 v[98:99], v[98:99], v[178:179], v[148:149] op_sel_hi:[1,0,1]
	v_lshl_add_u64 v[104:105], v[104:105], 0, v[126:127]
	v_pk_fma_f32 v[102:103], v[102:103], v[178:179], v[152:153] op_sel_hi:[1,0,1]
	v_pk_fma_f32 v[100:101], v[100:101], v[178:179], v[154:155] op_sel_hi:[1,0,1]
	v_pk_fma_f32 v[96:97], v[96:97], v[178:179], v[150:151] op_sel_hi:[1,0,1]
	v_max_f32_e32 v98, 0, v98
	v_cvt_pk_bf16_f32 v109, v114, v115
	global_store_dwordx4 v[104:105], v[106:109], off
	v_max_f32_e32 v100, 0, v100
	v_max_f32_e32 v96, 0, v96
	v_mul_f32_e32 v106, v98, v98
	v_max_f32_e32 v98, 0, v103
	v_mul_f32_e32 v100, v100, v100
	v_mul_f32_e32 v96, v96, v96
	v_max_f32_e32 v101, 0, v101
	v_max_f32_e32 v97, 0, v97
	v_max_f32_e32 v102, 0, v102
	v_mul_f32_e32 v103, v98, v98
	v_max_f32_e32 v98, 0, v99
	v_mul_f32_e32 v101, v101, v101
	v_mul_f32_e32 v97, v97, v97
	v_mul_f32_e32 v102, v102, v102
	v_mul_f32_e32 v107, v98, v98
	v_cvt_pk_bf16_f32 v98, v100, v101
	v_cvt_pk_bf16_f32 v99, v102, v103
	v_cvt_pk_bf16_f32 v100, v96, v97
	v_or_b32_e32 v96, 48, v146
	v_ashrrev_i32_e32 v97, 31, v96
	v_lshlrev_b64 v[96:97], 13, v[96:97]
	v_lshl_add_u64 v[96:97], s[8:9], 0, v[96:97]
	v_pk_fma_f32 v[90:91], v[90:91], v[176:177], v[148:149] op_sel_hi:[1,0,1]
	v_lshl_add_u64 v[96:97], v[96:97], 0, v[126:127]
	v_pk_fma_f32 v[94:95], v[94:95], v[176:177], v[152:153] op_sel_hi:[1,0,1]
	v_max_f32_e32 v90, 0, v90
	v_cvt_pk_bf16_f32 v101, v106, v107
	global_store_dwordx4 v[96:97], v[98:101], off
	v_pk_fma_f32 v[92:93], v[92:93], v[176:177], v[154:155] op_sel_hi:[1,0,1]
	v_max_f32_e32 v94, 0, v94
	v_mul_f32_e32 v98, v90, v90
	v_max_f32_e32 v90, 0, v95
	v_max_f32_e32 v92, 0, v92
	v_max_f32_e32 v93, 0, v93
	v_mul_f32_e32 v94, v94, v94
	v_mul_f32_e32 v95, v90, v90
	v_max_f32_e32 v90, 0, v91
	v_pk_fma_f32 v[88:89], v[88:89], v[176:177], v[150:151] op_sel_hi:[1,0,1]
	v_mul_f32_e32 v92, v92, v92
	v_mul_f32_e32 v93, v93, v93
	v_mul_f32_e32 v99, v90, v90
	v_cvt_pk_bf16_f32 v90, v92, v93
	v_cvt_pk_bf16_f32 v91, v94, v95
	v_add_co_u32_e32 v94, vcc, s1, v120
	v_pk_fma_f32 v[82:83], v[82:83], v[174:175], v[148:149] op_sel_hi:[1,0,1]
	v_max_f32_e32 v88, 0, v88
	v_max_f32_e32 v89, 0, v89
	v_addc_co_u32_e32 v95, vcc, 0, v121, vcc
	v_pk_fma_f32 v[86:87], v[86:87], v[174:175], v[152:153] op_sel_hi:[1,0,1]
	v_max_f32_e32 v82, 0, v82
	v_mul_f32_e32 v88, v88, v88
	v_mul_f32_e32 v89, v89, v89
	v_cvt_pk_bf16_f32 v92, v88, v89
	v_cvt_pk_bf16_f32 v93, v98, v99
	global_store_dwordx4 v[94:95], v[90:93], off
	v_pk_fma_f32 v[84:85], v[84:85], v[174:175], v[154:155] op_sel_hi:[1,0,1]
	v_max_f32_e32 v86, 0, v86
	v_mul_f32_e32 v90, v82, v82
	v_max_f32_e32 v82, 0, v87
	v_max_f32_e32 v84, 0, v84
	v_max_f32_e32 v85, 0, v85
	v_mul_f32_e32 v86, v86, v86
	v_mul_f32_e32 v87, v82, v82
	v_max_f32_e32 v82, 0, v83
	s_mov_b32 s1, 0x120000
	v_pk_fma_f32 v[80:81], v[80:81], v[174:175], v[150:151] op_sel_hi:[1,0,1]
	v_mul_f32_e32 v84, v84, v84
	v_mul_f32_e32 v85, v85, v85
	v_mul_f32_e32 v91, v82, v82
	v_cvt_pk_bf16_f32 v82, v84, v85
	v_cvt_pk_bf16_f32 v83, v86, v87
	v_add_co_u32_e32 v86, vcc, s1, v120
	v_pk_fma_f32 v[74:75], v[74:75], v[172:173], v[148:149] op_sel_hi:[1,0,1]
	v_max_f32_e32 v80, 0, v80
	v_max_f32_e32 v81, 0, v81
	v_addc_co_u32_e32 v87, vcc, 0, v121, vcc
	v_pk_fma_f32 v[78:79], v[78:79], v[172:173], v[152:153] op_sel_hi:[1,0,1]
	v_max_f32_e32 v74, 0, v74
	v_mul_f32_e32 v80, v80, v80
	v_mul_f32_e32 v81, v81, v81
	v_cvt_pk_bf16_f32 v84, v80, v81
	v_cvt_pk_bf16_f32 v85, v90, v91
	global_store_dwordx4 v[86:87], v[82:85], off
	v_pk_fma_f32 v[76:77], v[76:77], v[172:173], v[154:155] op_sel_hi:[1,0,1]
	v_max_f32_e32 v78, 0, v78
	v_mul_f32_e32 v82, v74, v74
	v_max_f32_e32 v74, 0, v79
	v_max_f32_e32 v76, 0, v76
	v_max_f32_e32 v77, 0, v77
	v_mul_f32_e32 v78, v78, v78
	v_mul_f32_e32 v79, v74, v74
	v_max_f32_e32 v74, 0, v75
	s_mov_b32 s1, 0x140000
	v_pk_fma_f32 v[72:73], v[72:73], v[172:173], v[150:151] op_sel_hi:[1,0,1]
	v_mul_f32_e32 v76, v76, v76
	v_mul_f32_e32 v77, v77, v77
	v_mul_f32_e32 v83, v74, v74
	v_cvt_pk_bf16_f32 v74, v76, v77
	v_cvt_pk_bf16_f32 v75, v78, v79
	v_add_co_u32_e32 v78, vcc, s1, v120
	v_pk_fma_f32 v[58:59], v[58:59], v[158:159], v[148:149] op_sel_hi:[1,0,1]
	v_max_f32_e32 v72, 0, v72
	v_max_f32_e32 v73, 0, v73
	v_addc_co_u32_e32 v79, vcc, 0, v121, vcc
	v_pk_fma_f32 v[62:63], v[62:63], v[158:159], v[152:153] op_sel_hi:[1,0,1]
	v_max_f32_e32 v58, 0, v58
	v_mul_f32_e32 v72, v72, v72
	v_mul_f32_e32 v73, v73, v73
	v_cvt_pk_bf16_f32 v76, v72, v73
	v_cvt_pk_bf16_f32 v77, v82, v83
	global_store_dwordx4 v[78:79], v[74:77], off
	v_pk_fma_f32 v[60:61], v[60:61], v[158:159], v[154:155] op_sel_hi:[1,0,1]
	v_max_f32_e32 v62, 0, v62
	v_mul_f32_e32 v74, v58, v58
	v_max_f32_e32 v58, 0, v63
	v_max_f32_e32 v60, 0, v60
	v_max_f32_e32 v61, 0, v61
	v_mul_f32_e32 v62, v62, v62
	v_mul_f32_e32 v63, v58, v58
	v_max_f32_e32 v58, 0, v59
	s_mov_b32 s1, 0x160000
	v_pk_fma_f32 v[56:57], v[56:57], v[158:159], v[150:151] op_sel_hi:[1,0,1]
	v_mul_f32_e32 v60, v60, v60
	v_mul_f32_e32 v61, v61, v61
	v_mul_f32_e32 v75, v58, v58
	v_cvt_pk_bf16_f32 v58, v60, v61
	v_cvt_pk_bf16_f32 v59, v62, v63
	v_add_co_u32_e32 v62, vcc, s1, v120
	s_waitcnt vmcnt(7)
	v_pk_add_f32 v[134:135], v[134:135], 0 op_sel_hi:[1,0]
	v_max_f32_e32 v56, 0, v56
	v_max_f32_e32 v57, 0, v57
	v_addc_co_u32_e32 v63, vcc, 0, v121, vcc
	v_pk_add_f32 v[130:131], v[130:131], 0 op_sel_hi:[1,0]
	v_mul_f32_e32 v56, v56, v56
	v_mul_f32_e32 v57, v57, v57
	v_cvt_pk_bf16_f32 v60, v56, v57
	v_cvt_pk_bf16_f32 v61, v74, v75
	global_store_dwordx4 v[62:63], v[58:61], off
	v_pk_fma_f32 v[62:63], v[66:67], v[184:185], v[130:131] op_sel_hi:[1,0,1]
	v_pk_add_f32 v[132:133], v[132:133], 0 op_sel_hi:[1,0]
	v_pk_fma_f32 v[58:59], v[70:71], v[184:185], v[134:135] op_sel_hi:[1,0,1]
	v_pk_add_f32 v[128:129], v[128:129], 0 op_sel_hi:[1,0]
	v_max_f32_e32 v58, 0, v58
	v_mul_f32_e32 v66, v58, v58
	v_max_f32_e32 v58, 0, v62
	v_pk_fma_f32 v[60:61], v[68:69], v[184:185], v[132:133] op_sel_hi:[1,0,1]
	v_mul_f32_e32 v62, v58, v58
	v_max_f32_e32 v58, 0, v59
	v_pk_fma_f32 v[64:65], v[64:65], v[184:185], v[128:129] op_sel_hi:[1,0,1]
	v_max_f32_e32 v60, 0, v60
	v_max_f32_e32 v61, 0, v61
	v_mul_f32_e32 v59, v58, v58
	v_max_f32_e32 v58, 0, v63
	v_pk_fma_f32 v[48:49], v[48:49], v[182:183], v[128:129] op_sel_hi:[1,0,1]
	v_mul_f32_e32 v60, v60, v60
	v_max_f32_e32 v64, 0, v64
	v_mul_f32_e32 v61, v61, v61
	v_max_f32_e32 v65, 0, v65
	v_mul_f32_e32 v63, v58, v58
	v_cvt_pk_bf16_f32 v58, v60, v61
	v_pk_fma_f32 v[52:53], v[52:53], v[182:183], v[132:133] op_sel_hi:[1,0,1]
	v_pk_fma_f32 v[50:51], v[50:51], v[182:183], v[130:131] op_sel_hi:[1,0,1]
	v_max_f32_e32 v48, 0, v48
	v_mul_f32_e32 v64, v64, v64
	v_mul_f32_e32 v65, v65, v65
	v_cvt_pk_bf16_f32 v59, v66, v59
	v_cvt_pk_bf16_f32 v60, v64, v65
	v_cvt_pk_bf16_f32 v61, v62, v63
	global_store_dwordx4 v[120:121], v[58:61], off offset:256
	v_pk_fma_f32 v[54:55], v[54:55], v[182:183], v[134:135] op_sel_hi:[1,0,1]
	v_max_f32_e32 v49, 0, v49
	v_mul_f32_e32 v58, v48, v48
	v_max_f32_e32 v48, 0, v53
	v_max_f32_e32 v50, 0, v50
	v_max_f32_e32 v52, 0, v52
	v_mul_f32_e32 v48, v48, v48
	v_mul_f32_e32 v53, v49, v49
	v_max_f32_e32 v49, 0, v54
	v_mul_f32_e32 v54, v50, v50
	v_max_f32_e32 v50, 0, v55
	v_max_f32_e32 v51, 0, v51
	v_pk_fma_f32 v[40:41], v[40:41], v[180:181], v[128:129] op_sel_hi:[1,0,1]
	v_mul_f32_e32 v52, v52, v52
	v_mul_f32_e32 v49, v49, v49
	v_mul_f32_e32 v50, v50, v50
	v_mul_f32_e32 v51, v51, v51
	v_cvt_pk_bf16_f32 v48, v52, v48
	v_pk_fma_f32 v[44:45], v[44:45], v[180:181], v[132:133] op_sel_hi:[1,0,1]
	v_pk_fma_f32 v[42:43], v[42:43], v[180:181], v[130:131] op_sel_hi:[1,0,1]
	v_max_f32_e32 v40, 0, v40
	v_cvt_pk_bf16_f32 v49, v49, v50
	v_cvt_pk_bf16_f32 v50, v58, v53
	v_cvt_pk_bf16_f32 v51, v54, v51
	global_store_dwordx4 v[112:113], v[48:51], off offset:256
	v_pk_fma_f32 v[46:47], v[46:47], v[180:181], v[134:135] op_sel_hi:[1,0,1]
	v_max_f32_e32 v41, 0, v41
	v_mul_f32_e32 v48, v40, v40
	v_max_f32_e32 v40, 0, v45
	v_max_f32_e32 v42, 0, v42
	v_max_f32_e32 v44, 0, v44
	v_mul_f32_e32 v40, v40, v40
	v_mul_f32_e32 v45, v41, v41
	v_max_f32_e32 v41, 0, v46
	v_mul_f32_e32 v46, v42, v42
	v_max_f32_e32 v42, 0, v47
	v_max_f32_e32 v43, 0, v43
	v_pk_fma_f32 v[32:33], v[32:33], v[178:179], v[128:129] op_sel_hi:[1,0,1]
	v_mul_f32_e32 v44, v44, v44
	v_mul_f32_e32 v41, v41, v41
	v_mul_f32_e32 v42, v42, v42
	v_mul_f32_e32 v43, v43, v43
	v_cvt_pk_bf16_f32 v40, v44, v40
	v_pk_fma_f32 v[36:37], v[36:37], v[178:179], v[132:133] op_sel_hi:[1,0,1]
	v_pk_fma_f32 v[34:35], v[34:35], v[178:179], v[130:131] op_sel_hi:[1,0,1]
	v_max_f32_e32 v32, 0, v32
	v_cvt_pk_bf16_f32 v41, v41, v42
	v_cvt_pk_bf16_f32 v42, v48, v45
	v_cvt_pk_bf16_f32 v43, v46, v43
	global_store_dwordx4 v[104:105], v[40:43], off offset:256
	v_pk_fma_f32 v[38:39], v[38:39], v[178:179], v[134:135] op_sel_hi:[1,0,1]
	v_max_f32_e32 v33, 0, v33
	v_mul_f32_e32 v40, v32, v32
	v_max_f32_e32 v32, 0, v37
	v_max_f32_e32 v34, 0, v34
	v_max_f32_e32 v36, 0, v36
	v_mul_f32_e32 v32, v32, v32
	v_mul_f32_e32 v37, v33, v33
	v_max_f32_e32 v33, 0, v38
	v_mul_f32_e32 v38, v34, v34
	v_max_f32_e32 v34, 0, v39
	v_max_f32_e32 v35, 0, v35
	v_pk_fma_f32 v[24:25], v[24:25], v[176:177], v[128:129] op_sel_hi:[1,0,1]
	v_mul_f32_e32 v36, v36, v36
	v_mul_f32_e32 v33, v33, v33
	v_mul_f32_e32 v34, v34, v34
	v_mul_f32_e32 v35, v35, v35
	v_cvt_pk_bf16_f32 v32, v36, v32
	v_pk_fma_f32 v[28:29], v[28:29], v[176:177], v[132:133] op_sel_hi:[1,0,1]
	v_pk_fma_f32 v[26:27], v[26:27], v[176:177], v[130:131] op_sel_hi:[1,0,1]
	v_max_f32_e32 v24, 0, v24
	v_cvt_pk_bf16_f32 v33, v33, v34
	v_cvt_pk_bf16_f32 v34, v40, v37
	v_cvt_pk_bf16_f32 v35, v38, v35
	global_store_dwordx4 v[96:97], v[32:35], off offset:256
	v_pk_fma_f32 v[30:31], v[30:31], v[176:177], v[134:135] op_sel_hi:[1,0,1]
	v_max_f32_e32 v25, 0, v25
	v_mul_f32_e32 v32, v24, v24
	v_max_f32_e32 v24, 0, v29
	v_max_f32_e32 v26, 0, v26
	s_mov_b64 s[8:9], 0x100000
	v_max_f32_e32 v28, 0, v28
	v_mul_f32_e32 v24, v24, v24
	v_mul_f32_e32 v29, v25, v25
	v_max_f32_e32 v25, 0, v30
	v_mul_f32_e32 v30, v26, v26
	v_max_f32_e32 v26, 0, v31
	v_max_f32_e32 v27, 0, v27
	v_pk_fma_f32 v[16:17], v[16:17], v[174:175], v[128:129] op_sel_hi:[1,0,1]
	v_lshl_add_u64 v[88:89], v[120:121], 0, s[8:9]
	v_mul_f32_e32 v28, v28, v28
	v_mul_f32_e32 v25, v25, v25
	v_mul_f32_e32 v26, v26, v26
	v_mul_f32_e32 v27, v27, v27
	v_cvt_pk_bf16_f32 v24, v28, v24
	v_pk_fma_f32 v[20:21], v[20:21], v[174:175], v[132:133] op_sel_hi:[1,0,1]
	v_pk_fma_f32 v[18:19], v[18:19], v[174:175], v[130:131] op_sel_hi:[1,0,1]
	v_max_f32_e32 v16, 0, v16
	v_cvt_pk_bf16_f32 v25, v25, v26
	v_cvt_pk_bf16_f32 v26, v32, v29
	v_cvt_pk_bf16_f32 v27, v30, v27
	global_store_dwordx4 v[88:89], v[24:27], off offset:256
	v_pk_fma_f32 v[22:23], v[22:23], v[174:175], v[134:135] op_sel_hi:[1,0,1]
	v_max_f32_e32 v17, 0, v17
	v_mul_f32_e32 v24, v16, v16
	v_max_f32_e32 v16, 0, v21
	v_max_f32_e32 v18, 0, v18
	s_mov_b64 s[8:9], 0x120000
	v_max_f32_e32 v20, 0, v20
	v_mul_f32_e32 v16, v16, v16
	v_mul_f32_e32 v21, v17, v17
	v_max_f32_e32 v17, 0, v22
	v_mul_f32_e32 v22, v18, v18
	v_max_f32_e32 v18, 0, v23
	v_max_f32_e32 v19, 0, v19
	v_pk_fma_f32 v[8:9], v[8:9], v[172:173], v[128:129] op_sel_hi:[1,0,1]
	v_lshl_add_u64 v[80:81], v[120:121], 0, s[8:9]
	v_mul_f32_e32 v20, v20, v20
	v_mul_f32_e32 v17, v17, v17
	v_mul_f32_e32 v18, v18, v18
	v_mul_f32_e32 v19, v19, v19
	v_cvt_pk_bf16_f32 v16, v20, v16
	v_pk_fma_f32 v[12:13], v[12:13], v[172:173], v[132:133] op_sel_hi:[1,0,1]
	v_pk_fma_f32 v[10:11], v[10:11], v[172:173], v[130:131] op_sel_hi:[1,0,1]
	v_max_f32_e32 v8, 0, v8
	v_cvt_pk_bf16_f32 v17, v17, v18
	v_cvt_pk_bf16_f32 v18, v24, v21
	v_cvt_pk_bf16_f32 v19, v22, v19
	global_store_dwordx4 v[80:81], v[16:19], off offset:256
	v_pk_fma_f32 v[14:15], v[14:15], v[172:173], v[134:135] op_sel_hi:[1,0,1]
	v_max_f32_e32 v9, 0, v9
	v_mul_f32_e32 v16, v8, v8
	v_max_f32_e32 v8, 0, v13
	v_max_f32_e32 v10, 0, v10
	s_mov_b64 s[8:9], 0x140000
	v_max_f32_e32 v12, 0, v12
	v_mul_f32_e32 v8, v8, v8
	v_mul_f32_e32 v13, v9, v9
	v_max_f32_e32 v9, 0, v14
	v_mul_f32_e32 v14, v10, v10
	v_max_f32_e32 v10, 0, v15
	v_max_f32_e32 v11, 0, v11
	v_pk_fma_f32 v[2:3], v[2:3], v[158:159], v[130:131] op_sel_hi:[1,0,1]
	v_pk_fma_f32 v[0:1], v[0:1], v[158:159], v[128:129] op_sel_hi:[1,0,1]
	v_lshl_add_u64 v[72:73], v[120:121], 0, s[8:9]
	v_mul_f32_e32 v12, v12, v12
	v_mul_f32_e32 v9, v9, v9
	v_mul_f32_e32 v10, v10, v10
	v_mul_f32_e32 v11, v11, v11
	v_cvt_pk_bf16_f32 v8, v12, v8
	v_pk_fma_f32 v[6:7], v[6:7], v[158:159], v[134:135] op_sel_hi:[1,0,1]
	v_pk_fma_f32 v[4:5], v[4:5], v[158:159], v[132:133] op_sel_hi:[1,0,1]
	v_max_f32_e32 v0, 0, v0
	v_max_f32_e32 v1, 0, v1
	v_max_f32_e32 v2, 0, v2
	s_mov_b64 s[8:9], 0x160000
	v_cvt_pk_bf16_f32 v9, v9, v10
	v_cvt_pk_bf16_f32 v10, v16, v13
	v_cvt_pk_bf16_f32 v11, v14, v11
	global_store_dwordx4 v[72:73], v[8:11], off offset:256
	v_max_f32_e32 v3, 0, v3
	v_lshl_add_u64 v[56:57], v[120:121], 0, s[8:9]
	v_mul_f32_e32 v8, v0, v0
	v_max_f32_e32 v0, 0, v5
	v_mul_f32_e32 v5, v1, v1
	v_max_f32_e32 v1, 0, v6
	v_mul_f32_e32 v6, v2, v2
	v_max_f32_e32 v2, 0, v7
	v_max_f32_e32 v4, 0, v4
	v_mul_f32_e32 v0, v0, v0
	v_mul_f32_e32 v1, v1, v1
	v_mul_f32_e32 v2, v2, v2
	v_mul_f32_e32 v3, v3, v3
	s_and_b64 vcc, exec, s[2:3]
	s_mov_b64 s[8:9], s[58:59]
	v_mul_f32_e32 v4, v4, v4
	v_cvt_pk_bf16_f32 v0, v4, v0
	v_cvt_pk_bf16_f32 v1, v1, v2
	v_cvt_pk_bf16_f32 v2, v8, v5
	v_cvt_pk_bf16_f32 v3, v6, v3
	global_store_dwordx4 v[56:57], v[0:3], off offset:256
	s_cbranch_vccz .LBB0_343
	s_waitcnt vmcnt(0)
	s_mov_b32 s90, s62
	s_cmpk_gt_u32 s36, 0xff
	s_cbranch_scc1 .LBB0_354
	s_barrier
